# plus NA/SWA Q hoists, layer-0 wout epilogue ring prefetch, conv staging batched
# baseline (speedup 1.0000x reference)
.LBB0_480:
	v_lshl_add_u32 v8, s0, 6, v56
	s_mov_b32 s2, 0x10000
	v_cmp_gt_i32_e64 s[2:3], s2, v8
	v_mov_b32_e32 v14, 0
	v_mov_b32_e32 v15, 0
	v_cndmask_b32_e64 v9, v227, v252, s[2:3]
	v_and_b32_e32 v9, v9, v8
	v_add_u32_e32 v84, -15, v9
	v_cndmask_b32_e64 v83, v223, v230, s[2:3]
	v_sub_u32_e32 v82, v8, v9
	v_add_u32_e32 v206, v84, v57
	v_cmp_lt_u32_e64 s[2:3], v206, v83
	s_and_saveexec_b64 s[4:5], s[2:3]
	v_add_u32_e32 v8, v206, v82
	v_ashrrev_i32_e32 v9, 31, v8
	v_lshlrev_b64 v[8:9], 9, v[8:9]
	v_lshl_add_u64 v[10:11], v[18:19], 0, v[8:9]
	v_lshl_add_u64 v[12:13], v[20:21], 0, v[8:9]
	global_load_dwordx4 v[148:151], v[10:11], off
	global_load_dwordx4 v[152:155], v[12:13], off
	s_mov_b64 exec, s[4:5]
	v_add_u32_e32 v206, v84, v65
	v_cmp_lt_u32_e64 s[2:3], v206, v83
	s_and_saveexec_b64 s[4:5], s[2:3]
	v_add_u32_e32 v8, v206, v82
	v_ashrrev_i32_e32 v9, 31, v8
	v_lshlrev_b64 v[8:9], 9, v[8:9]
	v_lshl_add_u64 v[10:11], v[18:19], 0, v[8:9]
	v_lshl_add_u64 v[12:13], v[20:21], 0, v[8:9]
	global_load_dwordx4 v[156:159], v[10:11], off
	global_load_dwordx4 v[160:163], v[12:13], off
	s_mov_b64 exec, s[4:5]
	v_add_u32_e32 v206, v84, v66
	v_cmp_lt_u32_e64 s[2:3], v206, v83
	s_and_saveexec_b64 s[4:5], s[2:3]
	v_add_u32_e32 v8, v206, v82
	v_ashrrev_i32_e32 v9, 31, v8
	v_lshlrev_b64 v[8:9], 9, v[8:9]
	v_lshl_add_u64 v[10:11], v[18:19], 0, v[8:9]
	v_lshl_add_u64 v[12:13], v[20:21], 0, v[8:9]
	global_load_dwordx4 v[164:167], v[10:11], off
	global_load_dwordx4 v[168:171], v[12:13], off
	s_mov_b64 exec, s[4:5]
	v_add_u32_e32 v206, v84, v67
	v_cmp_lt_u32_e64 s[2:3], v206, v83
	s_and_saveexec_b64 s[4:5], s[2:3]
	v_add_u32_e32 v8, v206, v82
	v_ashrrev_i32_e32 v9, 31, v8
	v_lshlrev_b64 v[8:9], 9, v[8:9]
	v_lshl_add_u64 v[10:11], v[18:19], 0, v[8:9]
	v_lshl_add_u64 v[12:13], v[20:21], 0, v[8:9]
	global_load_dwordx4 v[172:175], v[10:11], off
	global_load_dwordx4 v[176:179], v[12:13], off
	s_mov_b64 exec, s[4:5]
	v_add_u32_e32 v206, v84, v68
	v_cmp_lt_u32_e64 s[2:3], v206, v83
	s_and_saveexec_b64 s[4:5], s[2:3]
	v_add_u32_e32 v8, v206, v82
	v_ashrrev_i32_e32 v9, 31, v8
	v_lshlrev_b64 v[8:9], 9, v[8:9]
	v_lshl_add_u64 v[10:11], v[18:19], 0, v[8:9]
	v_lshl_add_u64 v[12:13], v[20:21], 0, v[8:9]
	global_load_dwordx4 v[180:183], v[10:11], off
	global_load_dwordx4 v[184:187], v[12:13], off
	s_mov_b64 exec, s[4:5]
	v_add_u32_e32 v206, v84, v69
	v_cmp_lt_u32_e64 s[2:3], v206, v83
	s_and_saveexec_b64 s[4:5], s[2:3]
	v_add_u32_e32 v8, v206, v82
	v_ashrrev_i32_e32 v9, 31, v8
	v_lshlrev_b64 v[8:9], 9, v[8:9]
	v_lshl_add_u64 v[10:11], v[18:19], 0, v[8:9]
	v_lshl_add_u64 v[12:13], v[20:21], 0, v[8:9]
	global_load_dwordx4 v[188:191], v[10:11], off
	global_load_dwordx4 v[208:211], v[12:13], off
	s_mov_b64 exec, s[4:5]
	v_add_u32_e32 v206, v84, v70
	v_cmp_lt_u32_e64 s[2:3], v206, v83
	s_and_saveexec_b64 s[4:5], s[2:3]
	v_add_u32_e32 v8, v206, v82
	v_ashrrev_i32_e32 v9, 31, v8
	v_lshlrev_b64 v[8:9], 9, v[8:9]
	v_lshl_add_u64 v[10:11], v[18:19], 0, v[8:9]
	v_lshl_add_u64 v[12:13], v[20:21], 0, v[8:9]
	global_load_dwordx4 v[212:215], v[10:11], off
	global_load_dwordx4 v[216:219], v[12:13], off
	s_mov_b64 exec, s[4:5]
	v_add_u32_e32 v206, v84, v71
	v_cmp_lt_u32_e64 s[2:3], v206, v83
	s_and_b64 s[2:3], s[2:3], vcc
	s_and_saveexec_b64 s[4:5], s[2:3]
	v_add_u32_e32 v8, v206, v82
	v_ashrrev_i32_e32 v9, 31, v8
	v_lshlrev_b64 v[8:9], 9, v[8:9]
	v_lshl_add_u64 v[10:11], v[18:19], 0, v[8:9]
	v_lshl_add_u64 v[12:13], v[20:21], 0, v[8:9]
	global_load_dwordx4 v[244:247], v[10:11], off
	global_load_dwordx4 v[248:251], v[12:13], off
	s_mov_b64 exec, s[4:5]
	s_waitcnt vmcnt(0)
	v_mov_b64_e32 v[8:9], 0
	v_mov_b64_e32 v[10:11], 0
	v_mov_b64_e32 v[12:13], 0
	v_mov_b64_e32 v[14:15], 0
	v_add_u32_e32 v206, v84, v57
	v_cmp_lt_u32_e64 s[2:3], v206, v83
	s_and_saveexec_b64 s[4:5], s[2:3]
	v_lshlrev_b32_e32 v16, 16, v148
	v_and_b32_e32 v17, 0xffff0000, v148
	v_lshlrev_b32_e32 v146, 16, v152
	v_and_b32_e32 v147, 0xffff0000, v152
	v_pk_mul_f32 v[8:9], v[16:17], v[146:147]
	v_lshlrev_b32_e32 v16, 16, v149
	v_and_b32_e32 v17, 0xffff0000, v149
	v_lshlrev_b32_e32 v146, 16, v153
	v_and_b32_e32 v147, 0xffff0000, v153
	v_pk_mul_f32 v[10:11], v[16:17], v[146:147]
	v_lshlrev_b32_e32 v16, 16, v150
	v_and_b32_e32 v17, 0xffff0000, v150
	v_lshlrev_b32_e32 v146, 16, v154
	v_and_b32_e32 v147, 0xffff0000, v154
	v_pk_mul_f32 v[12:13], v[16:17], v[146:147]
	v_lshlrev_b32_e32 v16, 16, v151
	v_and_b32_e32 v17, 0xffff0000, v151
	v_lshlrev_b32_e32 v146, 16, v155
	v_and_b32_e32 v147, 0xffff0000, v155
	v_pk_mul_f32 v[14:15], v[16:17], v[146:147]
	s_mov_b64 exec, s[4:5]
	ds_write_b128 v74, v[8:11]
	ds_write_b128 v74, v[12:15] offset:16
	v_mov_b64_e32 v[86:87], 0
	v_mov_b64_e32 v[88:89], 0
	v_mov_b64_e32 v[90:91], 0
	v_mov_b64_e32 v[92:93], 0
	v_add_u32_e32 v206, v84, v65
	v_cmp_lt_u32_e64 s[2:3], v206, v83
	s_and_saveexec_b64 s[4:5], s[2:3]
	v_lshlrev_b32_e32 v16, 16, v156
	v_and_b32_e32 v17, 0xffff0000, v156
	v_lshlrev_b32_e32 v146, 16, v160
	v_and_b32_e32 v147, 0xffff0000, v160
	v_pk_mul_f32 v[86:87], v[16:17], v[146:147]
	v_lshlrev_b32_e32 v16, 16, v157
	v_and_b32_e32 v17, 0xffff0000, v157
	v_lshlrev_b32_e32 v146, 16, v161
	v_and_b32_e32 v147, 0xffff0000, v161
	v_pk_mul_f32 v[88:89], v[16:17], v[146:147]
	v_lshlrev_b32_e32 v16, 16, v158
	v_and_b32_e32 v17, 0xffff0000, v158
	v_lshlrev_b32_e32 v146, 16, v162
	v_and_b32_e32 v147, 0xffff0000, v162
	v_pk_mul_f32 v[90:91], v[16:17], v[146:147]
	v_lshlrev_b32_e32 v16, 16, v159
	v_and_b32_e32 v17, 0xffff0000, v159
	v_lshlrev_b32_e32 v146, 16, v163
	v_and_b32_e32 v147, 0xffff0000, v163
	v_pk_mul_f32 v[92:93], v[16:17], v[146:147]
	s_mov_b64 exec, s[4:5]
	ds_write_b128 v75, v[86:89]
	ds_write_b128 v75, v[90:93] offset:16
	v_mov_b64_e32 v[8:9], 0
	v_mov_b64_e32 v[10:11], 0
	v_mov_b64_e32 v[12:13], 0
	v_mov_b64_e32 v[14:15], 0
	v_add_u32_e32 v206, v84, v66
	v_cmp_lt_u32_e64 s[2:3], v206, v83
	s_and_saveexec_b64 s[4:5], s[2:3]
	v_lshlrev_b32_e32 v16, 16, v164
	v_and_b32_e32 v17, 0xffff0000, v164
	v_lshlrev_b32_e32 v146, 16, v168
	v_and_b32_e32 v147, 0xffff0000, v168
	v_pk_mul_f32 v[8:9], v[16:17], v[146:147]
	v_lshlrev_b32_e32 v16, 16, v165
	v_and_b32_e32 v17, 0xffff0000, v165
	v_lshlrev_b32_e32 v146, 16, v169
	v_and_b32_e32 v147, 0xffff0000, v169
	v_pk_mul_f32 v[10:11], v[16:17], v[146:147]
	v_lshlrev_b32_e32 v16, 16, v166
	v_and_b32_e32 v17, 0xffff0000, v166
	v_lshlrev_b32_e32 v146, 16, v170
	v_and_b32_e32 v147, 0xffff0000, v170
	v_pk_mul_f32 v[12:13], v[16:17], v[146:147]
	v_lshlrev_b32_e32 v16, 16, v167
	v_and_b32_e32 v17, 0xffff0000, v167
	v_lshlrev_b32_e32 v146, 16, v171
	v_and_b32_e32 v147, 0xffff0000, v171
	v_pk_mul_f32 v[14:15], v[16:17], v[146:147]
	s_mov_b64 exec, s[4:5]
	ds_write_b128 v76, v[8:11]
	ds_write_b128 v76, v[12:15] offset:16
	v_mov_b64_e32 v[86:87], 0
	v_mov_b64_e32 v[88:89], 0
	v_mov_b64_e32 v[90:91], 0
	v_mov_b64_e32 v[92:93], 0
	v_add_u32_e32 v206, v84, v67
	v_cmp_lt_u32_e64 s[2:3], v206, v83
	s_and_saveexec_b64 s[4:5], s[2:3]
	v_lshlrev_b32_e32 v16, 16, v172
	v_and_b32_e32 v17, 0xffff0000, v172
	v_lshlrev_b32_e32 v146, 16, v176
	v_and_b32_e32 v147, 0xffff0000, v176
	v_pk_mul_f32 v[86:87], v[16:17], v[146:147]
	v_lshlrev_b32_e32 v16, 16, v173
	v_and_b32_e32 v17, 0xffff0000, v173
	v_lshlrev_b32_e32 v146, 16, v177
	v_and_b32_e32 v147, 0xffff0000, v177
	v_pk_mul_f32 v[88:89], v[16:17], v[146:147]
	v_lshlrev_b32_e32 v16, 16, v174
	v_and_b32_e32 v17, 0xffff0000, v174
	v_lshlrev_b32_e32 v146, 16, v178
	v_and_b32_e32 v147, 0xffff0000, v178
	v_pk_mul_f32 v[90:91], v[16:17], v[146:147]
	v_lshlrev_b32_e32 v16, 16, v175
	v_and_b32_e32 v17, 0xffff0000, v175
	v_lshlrev_b32_e32 v146, 16, v179
	v_and_b32_e32 v147, 0xffff0000, v179
	v_pk_mul_f32 v[92:93], v[16:17], v[146:147]
	s_mov_b64 exec, s[4:5]
	ds_write_b128 v77, v[86:89]
	ds_write_b128 v77, v[90:93] offset:16
	v_mov_b64_e32 v[8:9], 0
	v_mov_b64_e32 v[10:11], 0
	v_mov_b64_e32 v[12:13], 0
	v_mov_b64_e32 v[14:15], 0
	v_add_u32_e32 v206, v84, v68
	v_cmp_lt_u32_e64 s[2:3], v206, v83
	s_and_saveexec_b64 s[4:5], s[2:3]
	v_lshlrev_b32_e32 v16, 16, v180
	v_and_b32_e32 v17, 0xffff0000, v180
	v_lshlrev_b32_e32 v146, 16, v184
	v_and_b32_e32 v147, 0xffff0000, v184
	v_pk_mul_f32 v[8:9], v[16:17], v[146:147]
	v_lshlrev_b32_e32 v16, 16, v181
	v_and_b32_e32 v17, 0xffff0000, v181
	v_lshlrev_b32_e32 v146, 16, v185
	v_and_b32_e32 v147, 0xffff0000, v185
	v_pk_mul_f32 v[10:11], v[16:17], v[146:147]
	v_lshlrev_b32_e32 v16, 16, v182
	v_and_b32_e32 v17, 0xffff0000, v182
	v_lshlrev_b32_e32 v146, 16, v186
	v_and_b32_e32 v147, 0xffff0000, v186
	v_pk_mul_f32 v[12:13], v[16:17], v[146:147]
	v_lshlrev_b32_e32 v16, 16, v183
	v_and_b32_e32 v17, 0xffff0000, v183
	v_lshlrev_b32_e32 v146, 16, v187
	v_and_b32_e32 v147, 0xffff0000, v187
	v_pk_mul_f32 v[14:15], v[16:17], v[146:147]
	s_mov_b64 exec, s[4:5]
	ds_write_b128 v78, v[8:11]
	ds_write_b128 v78, v[12:15] offset:16
	v_mov_b64_e32 v[86:87], 0
	v_mov_b64_e32 v[88:89], 0
	v_mov_b64_e32 v[90:91], 0
	v_mov_b64_e32 v[92:93], 0
	v_add_u32_e32 v206, v84, v69
	v_cmp_lt_u32_e64 s[2:3], v206, v83
	s_and_saveexec_b64 s[4:5], s[2:3]
	v_lshlrev_b32_e32 v16, 16, v188
	v_and_b32_e32 v17, 0xffff0000, v188
	v_lshlrev_b32_e32 v146, 16, v208
	v_and_b32_e32 v147, 0xffff0000, v208
	v_pk_mul_f32 v[86:87], v[16:17], v[146:147]
	v_lshlrev_b32_e32 v16, 16, v189
	v_and_b32_e32 v17, 0xffff0000, v189
	v_lshlrev_b32_e32 v146, 16, v209
	v_and_b32_e32 v147, 0xffff0000, v209
	v_pk_mul_f32 v[88:89], v[16:17], v[146:147]
	v_lshlrev_b32_e32 v16, 16, v190
	v_and_b32_e32 v17, 0xffff0000, v190
	v_lshlrev_b32_e32 v146, 16, v210
	v_and_b32_e32 v147, 0xffff0000, v210
	v_pk_mul_f32 v[90:91], v[16:17], v[146:147]
	v_lshlrev_b32_e32 v16, 16, v191
	v_and_b32_e32 v17, 0xffff0000, v191
	v_lshlrev_b32_e32 v146, 16, v211
	v_and_b32_e32 v147, 0xffff0000, v211
	v_pk_mul_f32 v[92:93], v[16:17], v[146:147]
	s_mov_b64 exec, s[4:5]
	ds_write_b128 v79, v[86:89]
	ds_write_b128 v79, v[90:93] offset:16
	v_mov_b64_e32 v[8:9], 0
	v_mov_b64_e32 v[10:11], 0
	v_mov_b64_e32 v[12:13], 0
	v_mov_b64_e32 v[14:15], 0
	v_add_u32_e32 v206, v84, v70
	v_cmp_lt_u32_e64 s[2:3], v206, v83
	s_and_saveexec_b64 s[4:5], s[2:3]
	v_lshlrev_b32_e32 v16, 16, v212
	v_and_b32_e32 v17, 0xffff0000, v212
	v_lshlrev_b32_e32 v146, 16, v216
	v_and_b32_e32 v147, 0xffff0000, v216
	v_pk_mul_f32 v[8:9], v[16:17], v[146:147]
	v_lshlrev_b32_e32 v16, 16, v213
	v_and_b32_e32 v17, 0xffff0000, v213
	v_lshlrev_b32_e32 v146, 16, v217
	v_and_b32_e32 v147, 0xffff0000, v217
	v_pk_mul_f32 v[10:11], v[16:17], v[146:147]
	v_lshlrev_b32_e32 v16, 16, v214
	v_and_b32_e32 v17, 0xffff0000, v214
	v_lshlrev_b32_e32 v146, 16, v218
	v_and_b32_e32 v147, 0xffff0000, v218
	v_pk_mul_f32 v[12:13], v[16:17], v[146:147]
	v_lshlrev_b32_e32 v16, 16, v215
	v_and_b32_e32 v17, 0xffff0000, v215
	v_lshlrev_b32_e32 v146, 16, v219
	v_and_b32_e32 v147, 0xffff0000, v219
	v_pk_mul_f32 v[14:15], v[16:17], v[146:147]
	s_mov_b64 exec, s[4:5]
	ds_write_b128 v80, v[8:11]
	ds_write_b128 v80, v[12:15] offset:16
	s_and_saveexec_b64 s[6:7], vcc
	v_mov_b64_e32 v[86:87], 0
	v_mov_b64_e32 v[88:89], 0
	v_mov_b64_e32 v[90:91], 0
	v_mov_b64_e32 v[92:93], 0
	v_add_u32_e32 v206, v84, v71
	v_cmp_lt_u32_e64 s[2:3], v206, v83
	s_and_saveexec_b64 s[4:5], s[2:3]
	v_lshlrev_b32_e32 v16, 16, v244
	v_and_b32_e32 v17, 0xffff0000, v244
	v_lshlrev_b32_e32 v146, 16, v248
	v_and_b32_e32 v147, 0xffff0000, v248
	v_pk_mul_f32 v[86:87], v[16:17], v[146:147]
	v_lshlrev_b32_e32 v16, 16, v245
	v_and_b32_e32 v17, 0xffff0000, v245
	v_lshlrev_b32_e32 v146, 16, v249
	v_and_b32_e32 v147, 0xffff0000, v249
	v_pk_mul_f32 v[88:89], v[16:17], v[146:147]
	v_lshlrev_b32_e32 v16, 16, v246
	v_and_b32_e32 v17, 0xffff0000, v246
	v_lshlrev_b32_e32 v146, 16, v250
	v_and_b32_e32 v147, 0xffff0000, v250
	v_pk_mul_f32 v[90:91], v[16:17], v[146:147]
	v_lshlrev_b32_e32 v16, 16, v247
	v_and_b32_e32 v17, 0xffff0000, v247
	v_lshlrev_b32_e32 v146, 16, v251
	v_and_b32_e32 v147, 0xffff0000, v251
	v_pk_mul_f32 v[92:93], v[16:17], v[146:147]
	s_mov_b64 exec, s[4:5]
	ds_write_b128 v81, v[86:89]
	ds_write_b128 v81, v[90:93] offset:16
	s_mov_b64 exec, s[6:7]
	s_waitcnt lgkmcnt(0)
	s_barrier
	ds_read2st64_b32 v[8:9], v58 offset1:4
	ds_read2st64_b32 v[10:11], v58 offset0:8 offset1:12
	ds_read2st64_b32 v[12:13], v58 offset0:16 offset1:20
	ds_read2st64_b32 v[14:15], v58 offset0:24 offset1:28
	ds_read2st64_b32 v[16:17], v58 offset0:32 offset1:36
	s_waitcnt vmcnt(2) lgkmcnt(4)
	v_fma_f32 v8, v8, v24, v55
	v_fmac_f32_e32 v8, v9, v25
	v_fma_f32 v9, v9, v24, v55
	s_waitcnt lgkmcnt(3)
	v_fmac_f32_e32 v8, v10, v26
	v_fmac_f32_e32 v9, v10, v25
	v_fma_f32 v10, v10, v24, v55
	v_fmac_f32_e32 v8, v11, v27
	v_fmac_f32_e32 v9, v11, v26
	v_fmac_f32_e32 v10, v11, v25
	v_fma_f32 v11, v11, v24, v55
	s_waitcnt lgkmcnt(2)
	v_fmac_f32_e32 v8, v12, v28
	v_fmac_f32_e32 v9, v12, v27
	v_fmac_f32_e32 v10, v12, v26
	v_fmac_f32_e32 v11, v12, v25
	v_fma_f32 v12, v12, v24, v55
	v_fmac_f32_e32 v8, v13, v29
	v_fmac_f32_e32 v9, v13, v28
	v_fmac_f32_e32 v10, v13, v27
	v_fmac_f32_e32 v11, v13, v26
	v_fmac_f32_e32 v12, v13, v25
	v_fma_f32 v13, v13, v24, v55
	ds_read2st64_b32 v[82:83], v58 offset0:40 offset1:44
	s_waitcnt lgkmcnt(2)
	v_fmac_f32_e32 v8, v14, v30
	v_fmac_f32_e32 v9, v14, v29
	v_fmac_f32_e32 v10, v14, v28
	v_fmac_f32_e32 v11, v14, v27
	v_fmac_f32_e32 v12, v14, v26
	v_fmac_f32_e32 v13, v14, v25
	v_fma_f32 v14, v14, v24, v55
	v_fmac_f32_e32 v8, v15, v31
	v_fmac_f32_e32 v9, v15, v30
	v_fmac_f32_e32 v10, v15, v29
	v_fmac_f32_e32 v11, v15, v28
	v_fmac_f32_e32 v12, v15, v27
	v_fmac_f32_e32 v13, v15, v26
	v_fmac_f32_e32 v14, v15, v25
	v_fma_f32 v15, v15, v24, v55
	ds_read2st64_b32 v[84:85], v58 offset0:48 offset1:52
	s_waitcnt lgkmcnt(2)
	v_fmac_f32_e32 v8, v16, v32
	v_fmac_f32_e32 v9, v16, v31
	v_fmac_f32_e32 v10, v16, v30
	v_fmac_f32_e32 v11, v16, v29
	v_fmac_f32_e32 v12, v16, v28
	v_fmac_f32_e32 v13, v16, v27
	v_fmac_f32_e32 v14, v16, v26
	v_fmac_f32_e32 v15, v16, v25
	v_fma_f32 v16, v16, v24, v55
	v_fmac_f32_e32 v8, v17, v33
	v_fmac_f32_e32 v9, v17, v32
	v_fmac_f32_e32 v10, v17, v31
	v_fmac_f32_e32 v11, v17, v30
	v_fmac_f32_e32 v12, v17, v29
	v_fmac_f32_e32 v13, v17, v28
	v_fmac_f32_e32 v14, v17, v27
	v_fmac_f32_e32 v15, v17, v26
	v_fmac_f32_e32 v16, v17, v25
	v_fma_f32 v17, v17, v24, v55
	ds_read2st64_b32 v[86:87], v58 offset0:56 offset1:60
	s_waitcnt lgkmcnt(2)
	v_fmac_f32_e32 v8, v82, v34
	v_fmac_f32_e32 v9, v82, v33
	v_fmac_f32_e32 v10, v82, v32
	v_fmac_f32_e32 v11, v82, v31
	v_fmac_f32_e32 v12, v82, v30
	v_fmac_f32_e32 v13, v82, v29
	v_fmac_f32_e32 v14, v82, v28
	v_fmac_f32_e32 v15, v82, v27
	v_fmac_f32_e32 v16, v82, v26
	v_fmac_f32_e32 v17, v82, v25
	v_fma_f32 v82, v82, v24, v55
	v_fmac_f32_e32 v8, v83, v35
	v_fmac_f32_e32 v9, v83, v34
	v_fmac_f32_e32 v10, v83, v33
	v_fmac_f32_e32 v11, v83, v32
	v_fmac_f32_e32 v12, v83, v31
	v_fmac_f32_e32 v13, v83, v30
	v_fmac_f32_e32 v14, v83, v29
	v_fmac_f32_e32 v15, v83, v28
	v_fmac_f32_e32 v16, v83, v27
	v_fmac_f32_e32 v17, v83, v26
	v_fmac_f32_e32 v82, v83, v25
	v_fma_f32 v83, v83, v24, v55
	ds_read2st64_b32 v[88:89], v58 offset0:64 offset1:68
	s_waitcnt lgkmcnt(2)
	v_fmac_f32_e32 v8, v84, v36
	v_fmac_f32_e32 v9, v84, v35
	v_fmac_f32_e32 v10, v84, v34
	v_fmac_f32_e32 v11, v84, v33
	v_fmac_f32_e32 v12, v84, v32
	v_fmac_f32_e32 v13, v84, v31
	v_fmac_f32_e32 v14, v84, v30
	v_fmac_f32_e32 v15, v84, v29
	v_fmac_f32_e32 v16, v84, v28
	v_fmac_f32_e32 v17, v84, v27
	v_fmac_f32_e32 v82, v84, v26
	v_fmac_f32_e32 v83, v84, v25
	v_fma_f32 v84, v84, v24, v55
	v_fmac_f32_e32 v8, v85, v37
	v_fmac_f32_e32 v9, v85, v36
	v_fmac_f32_e32 v10, v85, v35
	v_fmac_f32_e32 v11, v85, v34
	v_fmac_f32_e32 v12, v85, v33
	v_fmac_f32_e32 v13, v85, v32
	v_fmac_f32_e32 v14, v85, v31
	v_fmac_f32_e32 v15, v85, v30
	v_fmac_f32_e32 v16, v85, v29
	v_fmac_f32_e32 v17, v85, v28
	v_fmac_f32_e32 v82, v85, v27
	v_fmac_f32_e32 v83, v85, v26
	v_fmac_f32_e32 v84, v85, v25
	v_fma_f32 v85, v85, v24, v55
	ds_read2st64_b32 v[90:91], v58 offset0:72 offset1:76
	s_waitcnt lgkmcnt(2)
	v_fmac_f32_e32 v8, v86, v38
	v_fmac_f32_e32 v9, v86, v37
	v_fmac_f32_e32 v10, v86, v36
	v_fmac_f32_e32 v11, v86, v35
	v_fmac_f32_e32 v12, v86, v34
	v_fmac_f32_e32 v13, v86, v33
	v_fmac_f32_e32 v14, v86, v32
	v_fmac_f32_e32 v15, v86, v31
	v_fmac_f32_e32 v16, v86, v30
	v_fmac_f32_e32 v17, v86, v29
	v_fmac_f32_e32 v82, v86, v28
	v_fmac_f32_e32 v83, v86, v27
	v_fmac_f32_e32 v84, v86, v26
	v_fmac_f32_e32 v85, v86, v25
	v_fma_f32 v86, v86, v24, v55
	v_fmac_f32_e32 v8, v87, v39
	v_fmac_f32_e32 v9, v87, v38
	v_fmac_f32_e32 v10, v87, v37
	v_fmac_f32_e32 v11, v87, v36
	v_fmac_f32_e32 v12, v87, v35
	v_fmac_f32_e32 v13, v87, v34
	v_fmac_f32_e32 v14, v87, v33
	v_fmac_f32_e32 v15, v87, v32
	v_fmac_f32_e32 v16, v87, v31
	v_fmac_f32_e32 v17, v87, v30
	v_fmac_f32_e32 v82, v87, v29
	v_fmac_f32_e32 v83, v87, v28
	v_fmac_f32_e32 v84, v87, v27
	v_fmac_f32_e32 v85, v87, v26
	v_fmac_f32_e32 v86, v87, v25
	v_fma_f32 v87, v87, v24, v55
	ds_read2st64_b32 v[92:93], v58 offset0:80 offset1:84
	s_waitcnt lgkmcnt(2)
	v_fmac_f32_e32 v8, v88, v40
	v_fmac_f32_e32 v9, v88, v39
	v_fmac_f32_e32 v10, v88, v38
	v_fmac_f32_e32 v11, v88, v37
	v_fmac_f32_e32 v12, v88, v36
	v_fmac_f32_e32 v13, v88, v35
	v_fmac_f32_e32 v14, v88, v34
	v_fmac_f32_e32 v15, v88, v33
	v_fmac_f32_e32 v16, v88, v32
	v_fmac_f32_e32 v17, v88, v31
	v_fmac_f32_e32 v82, v88, v30
	v_fmac_f32_e32 v83, v88, v29
	v_fmac_f32_e32 v84, v88, v28
	v_fmac_f32_e32 v85, v88, v27
	v_fmac_f32_e32 v86, v88, v26
	v_fmac_f32_e32 v87, v88, v25
	v_fma_f32 v88, v88, v24, v55
	v_fmac_f32_e32 v8, v89, v41
	v_fmac_f32_e32 v9, v89, v40
	v_fmac_f32_e32 v10, v89, v39
	v_fmac_f32_e32 v11, v89, v38
	v_fmac_f32_e32 v12, v89, v37
	v_fmac_f32_e32 v13, v89, v36
	v_fmac_f32_e32 v14, v89, v35
	v_fmac_f32_e32 v15, v89, v34
	v_fmac_f32_e32 v16, v89, v33
	v_fmac_f32_e32 v17, v89, v32
	v_fmac_f32_e32 v82, v89, v31
	v_fmac_f32_e32 v83, v89, v30
	v_fmac_f32_e32 v84, v89, v29
	v_fmac_f32_e32 v85, v89, v28
	v_fmac_f32_e32 v86, v89, v27
	v_fmac_f32_e32 v87, v89, v26
	v_fmac_f32_e32 v88, v89, v25
	v_fma_f32 v89, v89, v24, v55
	ds_read2st64_b32 v[94:95], v58 offset0:88 offset1:92
	s_waitcnt lgkmcnt(2)
	v_fmac_f32_e32 v8, v90, v42
	v_fmac_f32_e32 v9, v90, v41
	v_fmac_f32_e32 v10, v90, v40
	v_fmac_f32_e32 v11, v90, v39
	v_fmac_f32_e32 v12, v90, v38
	v_fmac_f32_e32 v13, v90, v37
	v_fmac_f32_e32 v14, v90, v36
	v_fmac_f32_e32 v15, v90, v35
	v_fmac_f32_e32 v16, v90, v34
	v_fmac_f32_e32 v17, v90, v33
	v_fmac_f32_e32 v82, v90, v32
	v_fmac_f32_e32 v83, v90, v31
	v_fmac_f32_e32 v84, v90, v30
	v_fmac_f32_e32 v85, v90, v29
	v_fmac_f32_e32 v86, v90, v28
	v_fmac_f32_e32 v87, v90, v27
	v_fmac_f32_e32 v88, v90, v26
	v_fmac_f32_e32 v89, v90, v25
	v_fma_f32 v90, v90, v24, v55
	v_fmac_f32_e32 v8, v91, v43
	v_fmac_f32_e32 v9, v91, v42
	v_fmac_f32_e32 v10, v91, v41
	v_fmac_f32_e32 v11, v91, v40
	v_fmac_f32_e32 v12, v91, v39
	v_fmac_f32_e32 v13, v91, v38
	v_fmac_f32_e32 v14, v91, v37
	v_fmac_f32_e32 v15, v91, v36
	v_fmac_f32_e32 v16, v91, v35
	v_fmac_f32_e32 v17, v91, v34
	v_fmac_f32_e32 v82, v91, v33
	v_fmac_f32_e32 v83, v91, v32
	v_fmac_f32_e32 v84, v91, v31
	v_fmac_f32_e32 v85, v91, v30
	v_fmac_f32_e32 v86, v91, v29
	v_fmac_f32_e32 v87, v91, v28
	v_fmac_f32_e32 v88, v91, v27
	v_fmac_f32_e32 v89, v91, v26
	v_fmac_f32_e32 v90, v91, v25
	v_fma_f32 v91, v91, v24, v55
	ds_read2st64_b32 v[96:97], v58 offset0:96 offset1:100
	s_waitcnt lgkmcnt(2)
	v_fmac_f32_e32 v8, v92, v44
	v_fmac_f32_e32 v9, v92, v43
	v_fmac_f32_e32 v10, v92, v42
	v_fmac_f32_e32 v11, v92, v41
	v_fmac_f32_e32 v12, v92, v40
	v_fmac_f32_e32 v13, v92, v39
	v_fmac_f32_e32 v14, v92, v38
	v_fmac_f32_e32 v15, v92, v37
	v_fmac_f32_e32 v16, v92, v36
	v_fmac_f32_e32 v17, v92, v35
	v_fmac_f32_e32 v82, v92, v34
	v_fmac_f32_e32 v83, v92, v33
	v_fmac_f32_e32 v84, v92, v32
	v_fmac_f32_e32 v85, v92, v31
	v_fmac_f32_e32 v86, v92, v30
	v_fmac_f32_e32 v87, v92, v29
	v_fmac_f32_e32 v88, v92, v28
	v_fmac_f32_e32 v89, v92, v27
	v_fmac_f32_e32 v90, v92, v26
	v_fmac_f32_e32 v91, v92, v25
	v_fma_f32 v92, v92, v24, v55
	v_fmac_f32_e32 v8, v93, v45
	v_fmac_f32_e32 v9, v93, v44
	v_fmac_f32_e32 v10, v93, v43
	v_fmac_f32_e32 v11, v93, v42
	v_fmac_f32_e32 v12, v93, v41
	v_fmac_f32_e32 v13, v93, v40
	v_fmac_f32_e32 v14, v93, v39
	v_fmac_f32_e32 v15, v93, v38
	v_fmac_f32_e32 v16, v93, v37
	v_fmac_f32_e32 v17, v93, v36
	v_fmac_f32_e32 v82, v93, v35
	v_fmac_f32_e32 v83, v93, v34
	v_fmac_f32_e32 v84, v93, v33
	v_fmac_f32_e32 v85, v93, v32
	v_fmac_f32_e32 v86, v93, v31
	v_fmac_f32_e32 v87, v93, v30
	v_fmac_f32_e32 v88, v93, v29
	v_fmac_f32_e32 v89, v93, v28
	v_fmac_f32_e32 v90, v93, v27
	v_fmac_f32_e32 v91, v93, v26
	v_fmac_f32_e32 v92, v93, v25
	v_fma_f32 v93, v93, v24, v55
	ds_read2st64_b32 v[98:99], v58 offset0:104 offset1:108
	s_waitcnt lgkmcnt(2)
	v_fmac_f32_e32 v8, v94, v46
	v_fmac_f32_e32 v9, v94, v45
	v_fmac_f32_e32 v10, v94, v44
	v_fmac_f32_e32 v11, v94, v43
	v_fmac_f32_e32 v12, v94, v42
	v_fmac_f32_e32 v13, v94, v41
	v_fmac_f32_e32 v14, v94, v40
	v_fmac_f32_e32 v15, v94, v39
	v_fmac_f32_e32 v16, v94, v38
	v_fmac_f32_e32 v17, v94, v37
	v_fmac_f32_e32 v82, v94, v36
	v_fmac_f32_e32 v83, v94, v35
	v_fmac_f32_e32 v84, v94, v34
	v_fmac_f32_e32 v85, v94, v33
	v_fmac_f32_e32 v86, v94, v32
	v_fmac_f32_e32 v87, v94, v31
	v_fmac_f32_e32 v88, v94, v30
	v_fmac_f32_e32 v89, v94, v29
	v_fmac_f32_e32 v90, v94, v28
	v_fmac_f32_e32 v91, v94, v27
	v_fmac_f32_e32 v92, v94, v26
	v_fmac_f32_e32 v93, v94, v25
	v_fma_f32 v94, v94, v24, v55
	v_fmac_f32_e32 v8, v95, v47
	v_fmac_f32_e32 v9, v95, v46
	v_fmac_f32_e32 v10, v95, v45
	v_fmac_f32_e32 v11, v95, v44
	v_fmac_f32_e32 v12, v95, v43
	v_fmac_f32_e32 v13, v95, v42
	v_fmac_f32_e32 v14, v95, v41
	v_fmac_f32_e32 v15, v95, v40
	v_fmac_f32_e32 v16, v95, v39
	v_fmac_f32_e32 v17, v95, v38
	v_fmac_f32_e32 v82, v95, v37
	v_fmac_f32_e32 v83, v95, v36
	v_fmac_f32_e32 v84, v95, v35
	v_fmac_f32_e32 v85, v95, v34
	v_fmac_f32_e32 v86, v95, v33
	v_fmac_f32_e32 v87, v95, v32
	v_fmac_f32_e32 v88, v95, v31
	v_fmac_f32_e32 v89, v95, v30
	v_fmac_f32_e32 v90, v95, v29
	v_fmac_f32_e32 v91, v95, v28
	v_fmac_f32_e32 v92, v95, v27
	v_fmac_f32_e32 v93, v95, v26
	v_fmac_f32_e32 v94, v95, v25
	v_fma_f32 v95, v95, v24, v55
	ds_read2st64_b32 v[100:101], v58 offset0:112 offset1:116
	s_waitcnt lgkmcnt(2)
	v_fmac_f32_e32 v8, v96, v48
	v_fmac_f32_e32 v9, v96, v47
	v_fmac_f32_e32 v10, v96, v46
	v_fmac_f32_e32 v11, v96, v45
	v_fmac_f32_e32 v12, v96, v44
	v_fmac_f32_e32 v13, v96, v43
	v_fmac_f32_e32 v14, v96, v42
	v_fmac_f32_e32 v15, v96, v41
	v_fmac_f32_e32 v16, v96, v40
	v_fmac_f32_e32 v17, v96, v39
	v_fmac_f32_e32 v82, v96, v38
	v_fmac_f32_e32 v83, v96, v37
	v_fmac_f32_e32 v84, v96, v36
	v_fmac_f32_e32 v85, v96, v35
	v_fmac_f32_e32 v86, v96, v34
	v_fmac_f32_e32 v87, v96, v33
	v_fmac_f32_e32 v88, v96, v32
	v_fmac_f32_e32 v89, v96, v31
	v_fmac_f32_e32 v90, v96, v30
	v_fmac_f32_e32 v91, v96, v29
	v_fmac_f32_e32 v92, v96, v28
	v_fmac_f32_e32 v93, v96, v27
	v_fmac_f32_e32 v94, v96, v26
	v_fmac_f32_e32 v95, v96, v25
	v_fma_f32 v96, v96, v24, v55
	v_fmac_f32_e32 v8, v97, v49
	v_fmac_f32_e32 v9, v97, v48
	v_fmac_f32_e32 v10, v97, v47
	v_fmac_f32_e32 v11, v97, v46
	v_fmac_f32_e32 v12, v97, v45
	v_fmac_f32_e32 v13, v97, v44
	v_fmac_f32_e32 v14, v97, v43
	v_fmac_f32_e32 v15, v97, v42
	v_fmac_f32_e32 v16, v97, v41
	v_fmac_f32_e32 v17, v97, v40
	v_fmac_f32_e32 v82, v97, v39
	v_fmac_f32_e32 v83, v97, v38
	v_fmac_f32_e32 v84, v97, v37
	v_fmac_f32_e32 v85, v97, v36
	v_fmac_f32_e32 v86, v97, v35
	v_fmac_f32_e32 v87, v97, v34
	v_fmac_f32_e32 v88, v97, v33
	v_fmac_f32_e32 v89, v97, v32
	v_fmac_f32_e32 v90, v97, v31
	v_fmac_f32_e32 v91, v97, v30
	v_fmac_f32_e32 v92, v97, v29
	v_fmac_f32_e32 v93, v97, v28
	v_fmac_f32_e32 v94, v97, v27
	v_fmac_f32_e32 v95, v97, v26
	v_fmac_f32_e32 v96, v97, v25
	v_fma_f32 v97, v97, v24, v55
	ds_read2st64_b32 v[102:103], v58 offset0:120 offset1:124
	s_waitcnt lgkmcnt(2)
	v_fmac_f32_e32 v8, v98, v50
	v_fmac_f32_e32 v9, v98, v49
	v_fmac_f32_e32 v10, v98, v48
	v_fmac_f32_e32 v11, v98, v47
	v_fmac_f32_e32 v12, v98, v46
	v_fmac_f32_e32 v13, v98, v45
	v_fmac_f32_e32 v14, v98, v44
	v_fmac_f32_e32 v15, v98, v43
	v_fmac_f32_e32 v16, v98, v42
	v_fmac_f32_e32 v17, v98, v41
	v_fmac_f32_e32 v82, v98, v40
	v_fmac_f32_e32 v83, v98, v39
	v_fmac_f32_e32 v84, v98, v38
	v_fmac_f32_e32 v85, v98, v37
	v_fmac_f32_e32 v86, v98, v36
	v_fmac_f32_e32 v87, v98, v35
	v_fmac_f32_e32 v88, v98, v34
	v_fmac_f32_e32 v89, v98, v33
	v_fmac_f32_e32 v90, v98, v32
	v_fmac_f32_e32 v91, v98, v31
	v_fmac_f32_e32 v92, v98, v30
	v_fmac_f32_e32 v93, v98, v29
	v_fmac_f32_e32 v94, v98, v28
	v_fmac_f32_e32 v95, v98, v27
	v_fmac_f32_e32 v96, v98, v26
	v_fmac_f32_e32 v97, v98, v25
	v_fma_f32 v98, v98, v24, v55
	v_fmac_f32_e32 v8, v99, v51
	v_fmac_f32_e32 v9, v99, v50
	v_fmac_f32_e32 v10, v99, v49
	v_fmac_f32_e32 v11, v99, v48
	v_fmac_f32_e32 v12, v99, v47
	v_fmac_f32_e32 v13, v99, v46
	v_fmac_f32_e32 v14, v99, v45
	v_fmac_f32_e32 v15, v99, v44
	v_fmac_f32_e32 v16, v99, v43
	v_fmac_f32_e32 v17, v99, v42
	v_fmac_f32_e32 v82, v99, v41
	v_fmac_f32_e32 v83, v99, v40
	v_fmac_f32_e32 v84, v99, v39
	v_fmac_f32_e32 v85, v99, v38
	v_fmac_f32_e32 v86, v99, v37
	v_fmac_f32_e32 v87, v99, v36
	v_fmac_f32_e32 v88, v99, v35
	v_fmac_f32_e32 v89, v99, v34
	v_fmac_f32_e32 v90, v99, v33
	v_fmac_f32_e32 v91, v99, v32
	v_fmac_f32_e32 v92, v99, v31
	v_fmac_f32_e32 v93, v99, v30
	v_fmac_f32_e32 v94, v99, v29
	v_fmac_f32_e32 v95, v99, v28
	v_fmac_f32_e32 v96, v99, v27
	v_fmac_f32_e32 v97, v99, v26
	v_fmac_f32_e32 v98, v99, v25
	v_fma_f32 v99, v99, v24, v55
	ds_read2st64_b32 v[104:105], v58 offset0:128 offset1:132
	s_waitcnt lgkmcnt(2)
	v_fmac_f32_e32 v8, v100, v52
	v_fmac_f32_e32 v9, v100, v51
	v_fmac_f32_e32 v10, v100, v50
	v_fmac_f32_e32 v11, v100, v49
	v_fmac_f32_e32 v12, v100, v48
	v_fmac_f32_e32 v13, v100, v47
	v_fmac_f32_e32 v14, v100, v46
	v_fmac_f32_e32 v15, v100, v45
	v_fmac_f32_e32 v16, v100, v44
	v_fmac_f32_e32 v17, v100, v43
	v_fmac_f32_e32 v82, v100, v42
	v_fmac_f32_e32 v83, v100, v41
	v_fmac_f32_e32 v84, v100, v40
	v_fmac_f32_e32 v85, v100, v39
	v_fmac_f32_e32 v86, v100, v38
	v_fmac_f32_e32 v87, v100, v37
	v_fmac_f32_e32 v88, v100, v36
	v_fmac_f32_e32 v89, v100, v35
	v_fmac_f32_e32 v90, v100, v34
	v_fmac_f32_e32 v91, v100, v33
	v_fmac_f32_e32 v92, v100, v32
	v_fmac_f32_e32 v93, v100, v31
	v_fmac_f32_e32 v94, v100, v30
	v_fmac_f32_e32 v95, v100, v29
	v_fmac_f32_e32 v96, v100, v28
	v_fmac_f32_e32 v97, v100, v27
	v_fmac_f32_e32 v98, v100, v26
	v_fmac_f32_e32 v99, v100, v25
	v_fma_f32 v100, v100, v24, v55
	v_fmac_f32_e32 v8, v101, v53
	v_fmac_f32_e32 v9, v101, v52
	v_fmac_f32_e32 v10, v101, v51
	v_fmac_f32_e32 v11, v101, v50
	v_fmac_f32_e32 v12, v101, v49
	v_fmac_f32_e32 v13, v101, v48
	v_fmac_f32_e32 v14, v101, v47
	v_fmac_f32_e32 v15, v101, v46
	v_fmac_f32_e32 v16, v101, v45
	v_fmac_f32_e32 v17, v101, v44
	v_fmac_f32_e32 v82, v101, v43
	v_fmac_f32_e32 v83, v101, v42
	v_fmac_f32_e32 v84, v101, v41
	v_fmac_f32_e32 v85, v101, v40
	v_fmac_f32_e32 v86, v101, v39
	v_fmac_f32_e32 v87, v101, v38
	v_fmac_f32_e32 v88, v101, v37
	v_fmac_f32_e32 v89, v101, v36
	v_fmac_f32_e32 v90, v101, v35
	v_fmac_f32_e32 v91, v101, v34
	v_fmac_f32_e32 v92, v101, v33
	v_fmac_f32_e32 v93, v101, v32
	v_fmac_f32_e32 v94, v101, v31
	v_fmac_f32_e32 v95, v101, v30
	v_fmac_f32_e32 v96, v101, v29
	v_fmac_f32_e32 v97, v101, v28
	v_fmac_f32_e32 v98, v101, v27
	v_fmac_f32_e32 v99, v101, v26
	v_fmac_f32_e32 v100, v101, v25
	v_fma_f32 v101, v101, v24, v55
	s_waitcnt lgkmcnt(1)
	v_fmac_f32_e32 v8, v102, v54
	v_fmac_f32_e32 v9, v102, v53
	v_fmac_f32_e32 v10, v102, v52
	v_fmac_f32_e32 v11, v102, v51
	v_fmac_f32_e32 v12, v102, v50
	v_fmac_f32_e32 v13, v102, v49
	v_fmac_f32_e32 v14, v102, v48
	v_fmac_f32_e32 v15, v102, v47
	v_fmac_f32_e32 v16, v102, v46
	v_fmac_f32_e32 v17, v102, v45
	v_fmac_f32_e32 v82, v102, v44
	v_fmac_f32_e32 v83, v102, v43
	v_fmac_f32_e32 v84, v102, v42
	v_fmac_f32_e32 v85, v102, v41
	v_fmac_f32_e32 v86, v102, v40
	v_fmac_f32_e32 v87, v102, v39
	v_fmac_f32_e32 v88, v102, v38
	v_fmac_f32_e32 v89, v102, v37
	v_fmac_f32_e32 v90, v102, v36
	v_fmac_f32_e32 v91, v102, v35
	v_fmac_f32_e32 v92, v102, v34
	v_fmac_f32_e32 v93, v102, v33
	v_fmac_f32_e32 v94, v102, v32
	v_fmac_f32_e32 v95, v102, v31
	v_fmac_f32_e32 v96, v102, v30
	v_fmac_f32_e32 v97, v102, v29
	v_fmac_f32_e32 v98, v102, v28
	v_fmac_f32_e32 v99, v102, v27
	v_fmac_f32_e32 v100, v102, v26
	v_fmac_f32_e32 v101, v102, v25
	v_fma_f32 v102, v102, v24, v55
	v_fmac_f32_e32 v9, v103, v54
	v_fmac_f32_e32 v10, v103, v53
	v_fmac_f32_e32 v11, v103, v52
	v_fmac_f32_e32 v12, v103, v51
	v_fmac_f32_e32 v13, v103, v50
	v_fmac_f32_e32 v14, v103, v49
	v_fmac_f32_e32 v15, v103, v48
	v_fmac_f32_e32 v16, v103, v47
	v_fmac_f32_e32 v17, v103, v46
	v_fmac_f32_e32 v82, v103, v45
	v_fmac_f32_e32 v83, v103, v44
	v_fmac_f32_e32 v84, v103, v43
	v_fmac_f32_e32 v85, v103, v42
	v_fmac_f32_e32 v86, v103, v41
	v_fmac_f32_e32 v87, v103, v40
	v_fmac_f32_e32 v88, v103, v39
	v_fmac_f32_e32 v89, v103, v38
	v_fmac_f32_e32 v90, v103, v37
	v_fmac_f32_e32 v91, v103, v36
	v_fmac_f32_e32 v92, v103, v35
	v_fmac_f32_e32 v93, v103, v34
	v_fmac_f32_e32 v94, v103, v33
	v_fmac_f32_e32 v95, v103, v32
	v_fmac_f32_e32 v96, v103, v31
	v_fmac_f32_e32 v97, v103, v30
	v_fmac_f32_e32 v98, v103, v29
	v_fmac_f32_e32 v99, v103, v28
	v_fmac_f32_e32 v100, v103, v27
	v_fmac_f32_e32 v101, v103, v26
	v_fmac_f32_e32 v102, v103, v25
	v_fma_f32 v103, v103, v24, v55
	s_waitcnt lgkmcnt(0)
	v_fmac_f32_e32 v11, v104, v53
	v_fmac_f32_e32 v12, v104, v52
	v_fmac_f32_e32 v13, v104, v51
	v_fmac_f32_e32 v14, v104, v50
	v_fmac_f32_e32 v15, v104, v49
	v_fmac_f32_e32 v16, v104, v48
	v_fmac_f32_e32 v17, v104, v47
	v_fmac_f32_e32 v82, v104, v46
	v_fmac_f32_e32 v83, v104, v45
	v_fmac_f32_e32 v84, v104, v44
	v_fmac_f32_e32 v85, v104, v43
	v_fmac_f32_e32 v86, v104, v42
	v_fmac_f32_e32 v87, v104, v41
	v_fmac_f32_e32 v88, v104, v40
	v_fmac_f32_e32 v89, v104, v39
	v_fmac_f32_e32 v90, v104, v38
	v_fmac_f32_e32 v91, v104, v37
	v_fmac_f32_e32 v92, v104, v36
	v_fmac_f32_e32 v93, v104, v35
	v_fmac_f32_e32 v94, v104, v34
	v_fmac_f32_e32 v95, v104, v33
	v_fmac_f32_e32 v96, v104, v32
	v_fmac_f32_e32 v97, v104, v31
	v_fmac_f32_e32 v98, v104, v30
	v_fmac_f32_e32 v99, v104, v29
	v_fmac_f32_e32 v100, v104, v28
	v_fmac_f32_e32 v101, v104, v27
	v_fmac_f32_e32 v102, v104, v26
	v_fmac_f32_e32 v103, v104, v25
	v_fmac_f32_e32 v10, v104, v54
	v_fmac_f32_e32 v11, v105, v54
	v_fmac_f32_e32 v12, v105, v53
	v_fmac_f32_e32 v13, v105, v52
	v_fmac_f32_e32 v14, v105, v51
	v_fmac_f32_e32 v15, v105, v50
	v_fmac_f32_e32 v16, v105, v49
	v_fmac_f32_e32 v17, v105, v48
	v_fmac_f32_e32 v82, v105, v47
	v_fmac_f32_e32 v83, v105, v46
	v_fmac_f32_e32 v84, v105, v45
	v_fmac_f32_e32 v85, v105, v44
	v_fmac_f32_e32 v86, v105, v43
	v_fmac_f32_e32 v87, v105, v42
	v_fmac_f32_e32 v88, v105, v41
	v_fmac_f32_e32 v89, v105, v40
	v_fmac_f32_e32 v90, v105, v39
	v_fmac_f32_e32 v91, v105, v38
	v_fmac_f32_e32 v92, v105, v37
	v_fmac_f32_e32 v93, v105, v36
	v_fmac_f32_e32 v94, v105, v35
	v_fmac_f32_e32 v95, v105, v34
	v_fmac_f32_e32 v96, v105, v33
	v_fmac_f32_e32 v97, v105, v32
	v_fmac_f32_e32 v98, v105, v31
	v_fmac_f32_e32 v99, v105, v30
	v_fmac_f32_e32 v100, v105, v29
	v_fmac_f32_e32 v101, v105, v28
	v_fmac_f32_e32 v102, v105, v27
	v_fmac_f32_e32 v103, v105, v26
	ds_read2st64_b32 v[104:105], v58 offset0:136 offset1:140
	s_mov_b32 s4, 0
	s_waitcnt lgkmcnt(0)
	v_fmac_f32_e32 v13, v104, v53
	v_fmac_f32_e32 v14, v104, v52
	v_fmac_f32_e32 v15, v104, v51
	v_fmac_f32_e32 v16, v104, v50
	v_fmac_f32_e32 v17, v104, v49
	v_fmac_f32_e32 v82, v104, v48
	v_fmac_f32_e32 v83, v104, v47
	v_fmac_f32_e32 v84, v104, v46
	v_fmac_f32_e32 v85, v104, v45
	v_fmac_f32_e32 v86, v104, v44
	v_fmac_f32_e32 v87, v104, v43
	v_fmac_f32_e32 v88, v104, v42
	v_fmac_f32_e32 v89, v104, v41
	v_fmac_f32_e32 v90, v104, v40
	v_fmac_f32_e32 v91, v104, v39
	v_fmac_f32_e32 v92, v104, v38
	v_fmac_f32_e32 v93, v104, v37
	v_fmac_f32_e32 v94, v104, v36
	v_fmac_f32_e32 v95, v104, v35
	v_fmac_f32_e32 v96, v104, v34
	v_fmac_f32_e32 v97, v104, v33
	v_fmac_f32_e32 v98, v104, v32
	v_fmac_f32_e32 v99, v104, v31
	v_fmac_f32_e32 v100, v104, v30
	v_fmac_f32_e32 v101, v104, v29
	v_fmac_f32_e32 v102, v104, v28
	v_fmac_f32_e32 v103, v104, v27
	v_fmac_f32_e32 v12, v104, v54
	v_fmac_f32_e32 v13, v105, v54
	v_fmac_f32_e32 v14, v105, v53
	v_fmac_f32_e32 v15, v105, v52
	v_fmac_f32_e32 v16, v105, v51
	v_fmac_f32_e32 v17, v105, v50
	v_fmac_f32_e32 v82, v105, v49
	v_fmac_f32_e32 v83, v105, v48
	v_fmac_f32_e32 v84, v105, v47
	v_fmac_f32_e32 v85, v105, v46
	v_fmac_f32_e32 v86, v105, v45
	v_fmac_f32_e32 v87, v105, v44
	v_fmac_f32_e32 v88, v105, v43
	v_fmac_f32_e32 v89, v105, v42
	v_fmac_f32_e32 v90, v105, v41
	v_fmac_f32_e32 v91, v105, v40
	v_fmac_f32_e32 v92, v105, v39
	v_fmac_f32_e32 v93, v105, v38
	v_fmac_f32_e32 v94, v105, v37
	v_fmac_f32_e32 v95, v105, v36
	v_fmac_f32_e32 v96, v105, v35
	v_fmac_f32_e32 v97, v105, v34
	v_fmac_f32_e32 v98, v105, v33
	v_fmac_f32_e32 v99, v105, v32
	v_fmac_f32_e32 v100, v105, v31
	v_fmac_f32_e32 v101, v105, v30
	v_fmac_f32_e32 v102, v105, v29
	v_fmac_f32_e32 v103, v105, v28
	ds_read2st64_b32 v[104:105], v58 offset0:144 offset1:148
	s_waitcnt lgkmcnt(0)
	v_fmac_f32_e32 v15, v104, v53
	v_fmac_f32_e32 v16, v104, v52
	v_fmac_f32_e32 v17, v104, v51
	v_fmac_f32_e32 v82, v104, v50
	v_fmac_f32_e32 v83, v104, v49
	v_fmac_f32_e32 v84, v104, v48
	v_fmac_f32_e32 v85, v104, v47
	v_fmac_f32_e32 v86, v104, v46
	v_fmac_f32_e32 v87, v104, v45
	v_fmac_f32_e32 v88, v104, v44
	v_fmac_f32_e32 v89, v104, v43
	v_fmac_f32_e32 v90, v104, v42
	v_fmac_f32_e32 v91, v104, v41
	v_fmac_f32_e32 v92, v104, v40
	v_fmac_f32_e32 v93, v104, v39
	v_fmac_f32_e32 v94, v104, v38
	v_fmac_f32_e32 v95, v104, v37
	v_fmac_f32_e32 v96, v104, v36
	v_fmac_f32_e32 v97, v104, v35
	v_fmac_f32_e32 v98, v104, v34
	v_fmac_f32_e32 v99, v104, v33
	v_fmac_f32_e32 v100, v104, v32
	v_fmac_f32_e32 v101, v104, v31
	v_fmac_f32_e32 v102, v104, v30
	v_fmac_f32_e32 v103, v104, v29
	v_fmac_f32_e32 v14, v104, v54
	v_fmac_f32_e32 v15, v105, v54
	v_fmac_f32_e32 v16, v105, v53
	v_fmac_f32_e32 v17, v105, v52
	v_fmac_f32_e32 v82, v105, v51
	v_fmac_f32_e32 v83, v105, v50
	v_fmac_f32_e32 v84, v105, v49
	v_fmac_f32_e32 v85, v105, v48
	v_fmac_f32_e32 v86, v105, v47
	v_fmac_f32_e32 v87, v105, v46
	v_fmac_f32_e32 v88, v105, v45
	v_fmac_f32_e32 v89, v105, v44
	v_fmac_f32_e32 v90, v105, v43
	v_fmac_f32_e32 v91, v105, v42
	v_fmac_f32_e32 v92, v105, v41
	v_fmac_f32_e32 v93, v105, v40
	v_fmac_f32_e32 v94, v105, v39
	v_fmac_f32_e32 v95, v105, v38
	v_fmac_f32_e32 v96, v105, v37
	v_fmac_f32_e32 v97, v105, v36
	v_fmac_f32_e32 v98, v105, v35
	v_fmac_f32_e32 v99, v105, v34
	v_fmac_f32_e32 v100, v105, v33
	v_fmac_f32_e32 v101, v105, v32
	v_fmac_f32_e32 v102, v105, v31
	v_fmac_f32_e32 v103, v105, v30
	ds_read2st64_b32 v[104:105], v58 offset0:152 offset1:156
	s_waitcnt lgkmcnt(0)
	v_fmac_f32_e32 v17, v104, v53
	v_fmac_f32_e32 v82, v104, v52
	v_fmac_f32_e32 v83, v104, v51
	v_fmac_f32_e32 v84, v104, v50
	v_fmac_f32_e32 v85, v104, v49
	v_fmac_f32_e32 v86, v104, v48
	v_fmac_f32_e32 v87, v104, v47
	v_fmac_f32_e32 v88, v104, v46
	v_fmac_f32_e32 v89, v104, v45
	v_fmac_f32_e32 v90, v104, v44
	v_fmac_f32_e32 v91, v104, v43
	v_fmac_f32_e32 v92, v104, v42
	v_fmac_f32_e32 v93, v104, v41
	v_fmac_f32_e32 v94, v104, v40
	v_fmac_f32_e32 v95, v104, v39
	v_fmac_f32_e32 v96, v104, v38
	v_fmac_f32_e32 v97, v104, v37
	v_fmac_f32_e32 v98, v104, v36
	v_fmac_f32_e32 v99, v104, v35
	v_fmac_f32_e32 v100, v104, v34
	v_fmac_f32_e32 v101, v104, v33
	v_fmac_f32_e32 v102, v104, v32
	v_fmac_f32_e32 v103, v104, v31
	v_fmac_f32_e32 v16, v104, v54
	v_fmac_f32_e32 v17, v105, v54
	v_fmac_f32_e32 v82, v105, v53
	v_fmac_f32_e32 v83, v105, v52
	v_fmac_f32_e32 v84, v105, v51
	v_fmac_f32_e32 v85, v105, v50
	v_fmac_f32_e32 v86, v105, v49
	v_fmac_f32_e32 v87, v105, v48
	v_fmac_f32_e32 v88, v105, v47
	v_fmac_f32_e32 v89, v105, v46
	v_fmac_f32_e32 v90, v105, v45
	v_fmac_f32_e32 v91, v105, v44
	v_fmac_f32_e32 v92, v105, v43
	v_fmac_f32_e32 v93, v105, v42
	v_fmac_f32_e32 v94, v105, v41
	v_fmac_f32_e32 v95, v105, v40
	v_fmac_f32_e32 v96, v105, v39
	v_fmac_f32_e32 v97, v105, v38
	v_fmac_f32_e32 v98, v105, v37
	v_fmac_f32_e32 v99, v105, v36
	v_fmac_f32_e32 v100, v105, v35
	v_fmac_f32_e32 v101, v105, v34
	v_fmac_f32_e32 v102, v105, v33
	v_fmac_f32_e32 v103, v105, v32
	ds_read2st64_b32 v[104:105], v58 offset0:160 offset1:164
	s_waitcnt lgkmcnt(0)
	v_fmac_f32_e32 v83, v104, v53
	v_fmac_f32_e32 v84, v104, v52
	v_fmac_f32_e32 v85, v104, v51
	v_fmac_f32_e32 v86, v104, v50
	v_fmac_f32_e32 v87, v104, v49
	v_fmac_f32_e32 v88, v104, v48
	v_fmac_f32_e32 v89, v104, v47
	v_fmac_f32_e32 v90, v104, v46
	v_fmac_f32_e32 v91, v104, v45
	v_fmac_f32_e32 v92, v104, v44
	v_fmac_f32_e32 v93, v104, v43
	v_fmac_f32_e32 v94, v104, v42
	v_fmac_f32_e32 v95, v104, v41
	v_fmac_f32_e32 v96, v104, v40
	v_fmac_f32_e32 v97, v104, v39
	v_fmac_f32_e32 v98, v104, v38
	v_fmac_f32_e32 v99, v104, v37
	v_fmac_f32_e32 v100, v104, v36
	v_fmac_f32_e32 v101, v104, v35
	v_fmac_f32_e32 v102, v104, v34
	v_fmac_f32_e32 v103, v104, v33
	v_fmac_f32_e32 v82, v104, v54
	v_fmac_f32_e32 v83, v105, v54
	v_fmac_f32_e32 v84, v105, v53
	v_fmac_f32_e32 v85, v105, v52
	v_fmac_f32_e32 v86, v105, v51
	v_fmac_f32_e32 v87, v105, v50
	v_fmac_f32_e32 v88, v105, v49
	v_fmac_f32_e32 v89, v105, v48
	v_fmac_f32_e32 v90, v105, v47
	v_fmac_f32_e32 v91, v105, v46
	v_fmac_f32_e32 v92, v105, v45
	v_fmac_f32_e32 v93, v105, v44
	v_fmac_f32_e32 v94, v105, v43
	v_fmac_f32_e32 v95, v105, v42
	v_fmac_f32_e32 v96, v105, v41
	v_fmac_f32_e32 v97, v105, v40
	v_fmac_f32_e32 v98, v105, v39
	v_fmac_f32_e32 v99, v105, v38
	v_fmac_f32_e32 v100, v105, v37
	v_fmac_f32_e32 v101, v105, v36
	v_fmac_f32_e32 v102, v105, v35
	v_fmac_f32_e32 v103, v105, v34
	ds_read2st64_b32 v[104:105], v58 offset0:168 offset1:172
	s_waitcnt lgkmcnt(0)
	v_fmac_f32_e32 v85, v104, v53
	v_fmac_f32_e32 v86, v104, v52
	v_fmac_f32_e32 v87, v104, v51
	v_fmac_f32_e32 v88, v104, v50
	v_fmac_f32_e32 v89, v104, v49
	v_fmac_f32_e32 v90, v104, v48
	v_fmac_f32_e32 v91, v104, v47
	v_fmac_f32_e32 v92, v104, v46
	v_fmac_f32_e32 v93, v104, v45
	v_fmac_f32_e32 v94, v104, v44
	v_fmac_f32_e32 v95, v104, v43
	v_fmac_f32_e32 v96, v104, v42
	v_fmac_f32_e32 v97, v104, v41
	v_fmac_f32_e32 v98, v104, v40
	v_fmac_f32_e32 v99, v104, v39
	v_fmac_f32_e32 v100, v104, v38
	v_fmac_f32_e32 v101, v104, v37
	v_fmac_f32_e32 v102, v104, v36
	v_fmac_f32_e32 v103, v104, v35
	v_fmac_f32_e32 v84, v104, v54
	v_fmac_f32_e32 v85, v105, v54
	v_fmac_f32_e32 v86, v105, v53
	v_fmac_f32_e32 v87, v105, v52
	v_fmac_f32_e32 v88, v105, v51
	v_fmac_f32_e32 v89, v105, v50
	v_fmac_f32_e32 v90, v105, v49
	v_fmac_f32_e32 v91, v105, v48
	v_fmac_f32_e32 v92, v105, v47
	v_fmac_f32_e32 v93, v105, v46
	v_fmac_f32_e32 v94, v105, v45
	v_fmac_f32_e32 v95, v105, v44
	v_fmac_f32_e32 v96, v105, v43
	v_fmac_f32_e32 v97, v105, v42
	v_fmac_f32_e32 v98, v105, v41
	v_fmac_f32_e32 v99, v105, v40
	v_fmac_f32_e32 v100, v105, v39
	v_fmac_f32_e32 v101, v105, v38
	v_fmac_f32_e32 v102, v105, v37
	v_fmac_f32_e32 v103, v105, v36
	ds_read2st64_b32 v[104:105], v58 offset0:176 offset1:180
	s_waitcnt lgkmcnt(0)
	v_fmac_f32_e32 v87, v104, v53
	v_fmac_f32_e32 v88, v104, v52
	v_fmac_f32_e32 v89, v104, v51
	v_fmac_f32_e32 v90, v104, v50
	v_fmac_f32_e32 v91, v104, v49
	v_fmac_f32_e32 v92, v104, v48
	v_fmac_f32_e32 v93, v104, v47
	v_fmac_f32_e32 v94, v104, v46
	v_fmac_f32_e32 v95, v104, v45
	v_fmac_f32_e32 v96, v104, v44
	v_fmac_f32_e32 v97, v104, v43
	v_fmac_f32_e32 v98, v104, v42
	v_fmac_f32_e32 v99, v104, v41
	v_fmac_f32_e32 v100, v104, v40
	v_fmac_f32_e32 v101, v104, v39
	v_fmac_f32_e32 v102, v104, v38
	v_fmac_f32_e32 v103, v104, v37
	v_fmac_f32_e32 v86, v104, v54
	v_fmac_f32_e32 v87, v105, v54
	v_fmac_f32_e32 v88, v105, v53
	v_fmac_f32_e32 v89, v105, v52
	v_fmac_f32_e32 v90, v105, v51
	v_fmac_f32_e32 v91, v105, v50
	v_fmac_f32_e32 v92, v105, v49
	v_fmac_f32_e32 v93, v105, v48
	v_fmac_f32_e32 v94, v105, v47
	v_fmac_f32_e32 v95, v105, v46
	v_fmac_f32_e32 v96, v105, v45
	v_fmac_f32_e32 v97, v105, v44
	v_fmac_f32_e32 v98, v105, v43
	v_fmac_f32_e32 v99, v105, v42
	v_fmac_f32_e32 v100, v105, v41
	v_fmac_f32_e32 v101, v105, v40
	v_fmac_f32_e32 v102, v105, v39
	v_fmac_f32_e32 v103, v105, v38
	ds_read2st64_b32 v[104:105], v58 offset0:184 offset1:188
	s_waitcnt lgkmcnt(0)
	v_fmac_f32_e32 v89, v104, v53
	v_fmac_f32_e32 v90, v104, v52
	v_fmac_f32_e32 v91, v104, v51
	v_fmac_f32_e32 v92, v104, v50
	v_fmac_f32_e32 v93, v104, v49
	v_fmac_f32_e32 v94, v104, v48
	v_fmac_f32_e32 v95, v104, v47
	v_fmac_f32_e32 v96, v104, v46
	v_fmac_f32_e32 v97, v104, v45
	v_fmac_f32_e32 v98, v104, v44
	v_fmac_f32_e32 v99, v104, v43
	v_fmac_f32_e32 v100, v104, v42
	v_fmac_f32_e32 v101, v104, v41
	v_fmac_f32_e32 v102, v104, v40
	v_fmac_f32_e32 v103, v104, v39
	v_fmac_f32_e32 v88, v104, v54
	v_fmac_f32_e32 v89, v105, v54
	v_fmac_f32_e32 v90, v105, v53
	v_fmac_f32_e32 v91, v105, v52
	v_fmac_f32_e32 v92, v105, v51
	v_fmac_f32_e32 v93, v105, v50
	v_fmac_f32_e32 v94, v105, v49
	v_fmac_f32_e32 v95, v105, v48
	v_fmac_f32_e32 v96, v105, v47
	v_fmac_f32_e32 v97, v105, v46
	v_fmac_f32_e32 v98, v105, v45
	v_fmac_f32_e32 v99, v105, v44
	v_fmac_f32_e32 v100, v105, v43
	v_fmac_f32_e32 v101, v105, v42
	v_fmac_f32_e32 v102, v105, v41
	v_fmac_f32_e32 v103, v105, v40
	ds_read2st64_b32 v[104:105], v58 offset0:192 offset1:196
	s_waitcnt lgkmcnt(0)
	v_fmac_f32_e32 v91, v104, v53
	v_fmac_f32_e32 v92, v104, v52
	v_fmac_f32_e32 v93, v104, v51
	v_fmac_f32_e32 v94, v104, v50
	v_fmac_f32_e32 v95, v104, v49
	v_fmac_f32_e32 v96, v104, v48
	v_fmac_f32_e32 v97, v104, v47
	v_fmac_f32_e32 v98, v104, v46
	v_fmac_f32_e32 v99, v104, v45
	v_fmac_f32_e32 v100, v104, v44
	v_fmac_f32_e32 v101, v104, v43
	v_fmac_f32_e32 v102, v104, v42
	v_fmac_f32_e32 v103, v104, v41
	v_fmac_f32_e32 v90, v104, v54
	v_fmac_f32_e32 v91, v105, v54
	v_fmac_f32_e32 v92, v105, v53
	v_fmac_f32_e32 v93, v105, v52
	v_fmac_f32_e32 v94, v105, v51
	v_fmac_f32_e32 v95, v105, v50
	v_fmac_f32_e32 v96, v105, v49
	v_fmac_f32_e32 v97, v105, v48
	v_fmac_f32_e32 v98, v105, v47
	v_fmac_f32_e32 v99, v105, v46
	v_fmac_f32_e32 v100, v105, v45
	v_fmac_f32_e32 v101, v105, v44
	v_fmac_f32_e32 v102, v105, v43
	v_fmac_f32_e32 v103, v105, v42
	ds_read2st64_b32 v[104:105], v58 offset0:200 offset1:204
	s_waitcnt lgkmcnt(0)
	v_fmac_f32_e32 v93, v104, v53
	v_fmac_f32_e32 v94, v104, v52
	v_fmac_f32_e32 v95, v104, v51
	v_fmac_f32_e32 v96, v104, v50
	v_fmac_f32_e32 v97, v104, v49
	v_fmac_f32_e32 v98, v104, v48
	v_fmac_f32_e32 v99, v104, v47
	v_fmac_f32_e32 v100, v104, v46
	v_fmac_f32_e32 v101, v104, v45
	v_fmac_f32_e32 v102, v104, v44
	v_fmac_f32_e32 v103, v104, v43
	v_fmac_f32_e32 v92, v104, v54
	v_fmac_f32_e32 v93, v105, v54
	v_fmac_f32_e32 v94, v105, v53
	v_fmac_f32_e32 v95, v105, v52
	v_fmac_f32_e32 v96, v105, v51
	v_fmac_f32_e32 v97, v105, v50
	v_fmac_f32_e32 v98, v105, v49
	v_fmac_f32_e32 v99, v105, v48
	v_fmac_f32_e32 v100, v105, v47
	v_fmac_f32_e32 v101, v105, v46
	v_fmac_f32_e32 v102, v105, v45
	v_fmac_f32_e32 v103, v105, v44
	ds_read2st64_b32 v[104:105], v58 offset0:208 offset1:212
	s_waitcnt lgkmcnt(0)
	v_fmac_f32_e32 v95, v104, v53
	v_fmac_f32_e32 v96, v104, v52
	v_fmac_f32_e32 v97, v104, v51
	v_fmac_f32_e32 v98, v104, v50
	v_fmac_f32_e32 v99, v104, v49
	v_fmac_f32_e32 v100, v104, v48
	v_fmac_f32_e32 v101, v104, v47
	v_fmac_f32_e32 v102, v104, v46
	v_fmac_f32_e32 v103, v104, v45
	v_fmac_f32_e32 v94, v104, v54
	v_fmac_f32_e32 v95, v105, v54
	v_fmac_f32_e32 v96, v105, v53
	v_fmac_f32_e32 v97, v105, v52
	v_fmac_f32_e32 v98, v105, v51
	v_fmac_f32_e32 v99, v105, v50
	v_fmac_f32_e32 v100, v105, v49
	v_fmac_f32_e32 v101, v105, v48
	v_fmac_f32_e32 v102, v105, v47
	v_fmac_f32_e32 v103, v105, v46
	ds_read2st64_b32 v[104:105], v58 offset0:216 offset1:220
	s_waitcnt lgkmcnt(0)
	v_fmac_f32_e32 v97, v104, v53
	v_fmac_f32_e32 v98, v104, v52
	v_fmac_f32_e32 v99, v104, v51
	v_fmac_f32_e32 v100, v104, v50
	v_fmac_f32_e32 v101, v104, v49
	v_fmac_f32_e32 v102, v104, v48
	v_fmac_f32_e32 v103, v104, v47
	v_fmac_f32_e32 v96, v104, v54
	v_fmac_f32_e32 v97, v105, v54
	v_fmac_f32_e32 v98, v105, v53
	v_fmac_f32_e32 v99, v105, v52
	v_fmac_f32_e32 v100, v105, v51
	v_fmac_f32_e32 v101, v105, v50
	v_fmac_f32_e32 v102, v105, v49
	v_fmac_f32_e32 v103, v105, v48
	ds_read2st64_b32 v[104:105], v58 offset0:224 offset1:228
	s_waitcnt lgkmcnt(0)
	v_fmac_f32_e32 v99, v104, v53
	v_fmac_f32_e32 v100, v104, v52
	v_fmac_f32_e32 v101, v104, v51
	v_fmac_f32_e32 v102, v104, v50
	v_fmac_f32_e32 v103, v104, v49
	v_fmac_f32_e32 v98, v104, v54
	v_fmac_f32_e32 v99, v105, v54
	v_fmac_f32_e32 v100, v105, v53
	v_fmac_f32_e32 v101, v105, v52
	v_fmac_f32_e32 v102, v105, v51
	v_fmac_f32_e32 v103, v105, v50
	ds_read2st64_b32 v[104:105], v58 offset0:232 offset1:236
	s_waitcnt lgkmcnt(0)
	v_fmac_f32_e32 v101, v104, v53
	v_fmac_f32_e32 v102, v104, v52
	v_fmac_f32_e32 v103, v104, v51
	v_fmac_f32_e32 v100, v104, v54
	v_fmac_f32_e32 v101, v105, v54
	v_fmac_f32_e32 v102, v105, v53
	v_fmac_f32_e32 v103, v105, v52
	ds_read2st64_b32 v[104:105], v58 offset0:240 offset1:244
	s_waitcnt lgkmcnt(0)
	s_barrier
	v_fmac_f32_e32 v103, v104, v53
	v_fmac_f32_e32 v102, v104, v54
	v_fmac_f32_e32 v103, v105, v54
	ds_write2st64_b32 v58, v8, v9 offset1:4
	ds_write2st64_b32 v58, v10, v11 offset0:8 offset1:12
	ds_write2st64_b32 v58, v12, v13 offset0:16 offset1:20
	ds_write2st64_b32 v58, v14, v15 offset0:24 offset1:28
	ds_write2st64_b32 v58, v16, v17 offset0:32 offset1:36
	ds_write2st64_b32 v58, v82, v83 offset0:40 offset1:44
	ds_write2st64_b32 v58, v84, v85 offset0:48 offset1:52
	ds_write2st64_b32 v58, v86, v87 offset0:56 offset1:60
	ds_write2st64_b32 v58, v88, v89 offset0:64 offset1:68
	ds_write2st64_b32 v58, v90, v91 offset0:72 offset1:76
	ds_write2st64_b32 v58, v92, v93 offset0:80 offset1:84
	ds_write2st64_b32 v58, v94, v95 offset0:88 offset1:92
	ds_write2st64_b32 v58, v96, v97 offset0:96 offset1:100
	ds_write2st64_b32 v58, v98, v99 offset0:104 offset1:108
	ds_write2st64_b32 v58, v100, v101 offset0:112 offset1:116
	ds_write2st64_b32 v58, v102, v103 offset0:120 offset1:124
	v_mov_b32_e32 v8, v72
	s_waitcnt lgkmcnt(0)
	s_barrier
	s_waitcnt vmcnt(0)

.Lna_vwr_done:
.LBB0_531:
	v_add_u32_e32 v28, s17, v15
	v_lshlrev_b32_e32 v0, 6, v28
	v_lshl_or_b32 v30, s19, 4, v17
	v_add3_u32 v20, s6, v30, v0
	v_ashrrev_i32_e32 v21, 31, v20
	v_readlane_b32 s6, v254, 0
	v_lshlrev_b64 v[0:1], 9, v[20:21]
	v_readlane_b32 s7, v254, 1
	v_lshlrev_b32_e32 v192, 1, v14
	s_nop 0
	v_lshl_add_u64 v[0:1], s[6:7], 0, v[0:1]
	v_lshl_add_u64 v[0:1], v[18:19], 1, v[0:1]
	v_lshl_add_u64 v[0:1], v[0:1], 0, v[192:193]
	global_load_dwordx4 v[148:151], v[0:1], off
	global_load_dwordx4 v[152:155], v[0:1], off offset:64
	s_waitcnt lgkmcnt(0)
	s_barrier
	v_add_u32_e32 v8, -4, v28
	v_min_i32_e32 v8, s18, v8
	v_cmp_lt_i32_e32 vcc, 3, v28
	v_add_u32_e32 v32, s8, v14
	v_med3_i32 v35, v30, 8, 56
	v_cndmask_b32_e32 v29, 0, v8, vcc
	v_subrev_u32_e32 v8, s16, v29
	v_lshlrev_b32_e32 v86, 5, v8
	v_or_b32_e32 v8, v86, v31
	v_mad_u64_u32 v[22:23], s[6:7], v8, s79, v[16:17]
	ds_read2_b64 v[8:11], v22 offset1:1
	ds_read2_b64 v[24:27], v22 offset0:8 offset1:9
	v_sub_u32_e32 v23, v32, v35
	v_add_u32_e32 v23, 8, v23
	v_sub_u32_e32 v28, v29, v28
	s_movk_i32 s0, 0x7c
	v_cmp_gt_u32_e32 vcc, 16, v23
	v_mul_lo_u32 v23, v28, s0
	v_add_u32_e32 v33, 0x1f300, v23
	v_sub_u32_e32 v23, v32, v30
	v_med3_i32 v44, v23, -15, 15
	s_waitcnt vmcnt(0)
	v_mov_b32_e32 v4, v148
	v_mov_b32_e32 v5, v149
	v_mov_b32_e32 v6, v150
	v_mov_b32_e32 v7, v151
	v_mov_b32_e32 v0, v152
	v_mov_b32_e32 v1, v153
	v_mov_b32_e32 v2, v154
	v_mov_b32_e32 v3, v155
	s_waitcnt lgkmcnt(1)
	v_mfma_f32_16x16x32_bf16 v[8:11], v[8:11], v[4:7], 0
	s_waitcnt lgkmcnt(0)
	v_mfma_f32_16x16x32_bf16 v[8:11], v[24:27], v[0:3], v[8:11]
	v_mov_b32_e32 v24, 0xf149f2ca
	v_mov_b32_e32 v26, 0xf149f2ca
	s_and_saveexec_b64 s[6:7], vcc
	s_cbranch_execz .LBB0_533
	v_lshl_add_u32 v23, v44, 2, v33
	ds_read_b32 v23, v23 offset:928
	s_waitcnt lgkmcnt(0)
	s_nop 0
	v_add_f32_e32 v26, v8, v23

.LBB0_699:
	s_or_b64 exec, exec, s[2:3]
	v_add_u32_e32 v0, s15, v87
	v_ashrrev_i32_e32 v1, 31, v0
	v_lshlrev_b64 v[2:3], 9, v[0:1]
	v_lshlrev_b64 v[0:1], 11, v[0:1]
	v_lshl_add_u64 v[0:1], s[86:87], 0, v[0:1]
	v_mov_b32_e32 v19, v193
	v_lshl_add_u64 v[0:1], v[0:1], 0, v[18:19]
	s_mov_b64 s[2:3], 0xa000600
	v_lshl_add_u64 v[22:23], v[0:1], 0, s[2:3]
	v_add_u32_e32 v0, s14, v37
	v_cmp_lt_i32_e32 vcc, -1, v0
	v_cmp_gt_i32_e64 s[44:45], s12, v0
	v_readlane_b32 s4, v254, 53
	s_and_b64 s[2:3], vcc, s[44:45]
	v_readlane_b32 s5, v254, 54
	s_and_b64 s[66:67], s[2:3], s[4:5]
	v_readlane_b32 s4, v254, 55
	v_readlane_b32 s5, v254, 56
	s_and_b64 s[68:69], s[2:3], s[4:5]
	v_readlane_b32 s4, v254, 57
	v_readlane_b32 s5, v254, 58
	s_and_b64 s[70:71], s[2:3], s[4:5]
	v_readlane_b32 s4, v254, 59
	v_readlane_b32 s5, v254, 60
	s_and_b64 s[74:75], s[2:3], s[4:5]
	v_readlane_b32 s4, v254, 61
	v_add_u32_e32 v1, 32, v0
	v_readlane_b32 s5, v254, 62
	v_cmp_lt_i32_e32 vcc, -1, v1
	v_cmp_gt_i32_e64 s[44:45], s12, v1
	v_add_u32_e32 v1, 64, v0
	s_and_b64 s[76:77], s[2:3], s[4:5]
	v_readlane_b32 s4, v254, 63
	s_and_b64 s[88:89], vcc, s[44:45]
	v_cmp_lt_i32_e32 vcc, -1, v1
	v_cmp_gt_i32_e64 s[44:45], s12, v1
	v_add_u32_e32 v1, 0x60, v0
	v_readlane_b32 s5, v255, 0
	s_and_b64 s[90:91], vcc, s[44:45]
	v_cmp_lt_i32_e32 vcc, -1, v1
	v_cmp_gt_i32_e64 s[44:45], s12, v1
	v_add_u32_e32 v1, s13, v37
	s_and_b64 s[78:79], s[2:3], s[4:5]
	v_readlane_b32 s4, v255, 1
	s_and_b64 s[64:65], vcc, s[44:45]
	v_cmp_lt_i32_e32 vcc, -1, v1
	v_cmp_gt_i32_e64 s[44:45], s12, v1
	v_add_u32_e32 v1, 0xa0, v0
	v_readlane_b32 s5, v255, 2
	s_and_b64 s[42:43], vcc, s[44:45]
	v_cmp_lt_i32_e32 vcc, -1, v1
	v_cmp_gt_i32_e64 s[44:45], s12, v1
	v_add_u32_e32 v1, 0xc0, v0
	s_and_b64 s[80:81], s[2:3], s[4:5]
	v_readlane_b32 s4, v255, 3
	s_and_b64 s[40:41], vcc, s[44:45]
	v_cmp_lt_i32_e32 vcc, -1, v1
	v_cmp_gt_i32_e64 s[44:45], s12, v1
	v_add_u32_e32 v1, 0xe0, v0
	v_readlane_b32 s5, v255, 4
	s_and_b64 s[46:47], vcc, s[44:45]
	v_cmp_lt_i32_e32 vcc, -1, v1
	v_cmp_gt_i32_e64 s[44:45], s12, v1
	v_add_u32_e32 v0, 0x100, v0
	s_and_b64 s[82:83], s[2:3], s[4:5]
	s_and_b64 s[2:3], vcc, s[44:45]
	v_cmp_lt_i32_e32 vcc, -1, v0
	v_cmp_gt_i32_e64 s[44:45], s12, v0
	v_readlane_b32 s4, v255, 5
	s_and_b64 s[16:17], vcc, s[44:45]
	v_readlane_b32 s5, v255, 6
	s_and_b64 s[44:45], s[16:17], s[4:5]
	v_readlane_b32 s4, v255, 7
	v_readlane_b32 s6, v255, 9
	v_readlane_b32 s5, v255, 8
	v_readlane_b32 s7, v255, 10
	s_lshl_b32 s24, s0, 1
	v_lshl_add_u64 v[20:21], v[16:17], 0, v[2:3]
	s_and_b64 s[4:5], s[16:17], s[4:5]
	s_and_b64 s[6:7], s[16:17], s[6:7]
	s_and_b64 s[8:9], s[16:17], s[28:29]
	s_and_b64 s[10:11], s[16:17], s[30:31]
	s_and_b64 s[12:13], s[16:17], s[34:35]
	s_and_b64 s[14:15], s[16:17], s[36:37]
	s_and_b64 s[16:17], s[16:17], s[38:39]
	s_mov_b32 s97, 0
	s_mov_b64 s[20:21], -1
	s_lshl_b32 s98, s24, 7
	s_mov_b32 s99, 0
	v_lshl_add_u64 v[164:165], v[20:21], 0, s[98:99]
	global_load_dwordx4 v[148:151], v[164:165], off
	global_load_dwordx4 v[152:155], v[164:165], off offset:64
	global_load_dwordx4 v[156:159], v[164:165], off offset:128
	global_load_dwordx4 v[160:163], v[164:165], off offset:192
	s_waitcnt lgkmcnt(0)
	s_barrier
	s_branch .LBB0_701
.LBB0_700:
	s_or_b64 exec, exec, s[18:19]
	s_waitcnt vmcnt(0)
	v_max3_f32 v0, v19, v28, v24
	v_max3_f32 v0, v0, v26, v25
	v_max3_f32 v0, v0, v29, v27
	v_max3_f32 v0, v0, v31, v30
	v_max3_f32 v0, v0, v33, v32
	v_max3_f32 v0, v0, v35, v34
	v_max3_f32 v0, v0, v38, v36
	v_max3_f32 v0, v0, v40, v39
	v_max3_f32 v0, v0, v43, v41
	v_max3_f32 v0, v0, v45, v44
	v_max3_f32 v0, v0, v47, v46
	v_max3_f32 v0, v0, v49, v48
	v_max3_f32 v0, v0, v51, v50
	v_max3_f32 v0, v0, v53, v52
	v_max3_f32 v0, v0, v59, v58
	v_max3_f32 v0, v0, v66, v67
	v_max3_f32 v0, v0, v95, v94
	v_max3_f32 v0, v0, v97, v96
	v_max3_f32 v0, v0, v99, v98
	v_max3_f32 v0, v0, v101, v100
	v_max3_f32 v0, v0, v103, v102
	v_max3_f32 v0, v0, v105, v104
	v_max3_f32 v0, v0, v107, v106
	v_max3_f32 v0, v0, v109, v108
	v_max3_f32 v0, v0, v111, v110
	v_max3_f32 v0, v0, v113, v112
	v_max3_f32 v0, v0, v115, v114
	v_max3_f32 v0, v0, v117, v116
	v_max3_f32 v0, v0, v119, v118
	v_max3_f32 v0, v0, v121, v120
	v_max3_f32 v0, v0, v123, v122
	v_max3_f32 v0, v0, v125, v124
	v_max3_f32 v0, v0, v127, v126
	v_add_u32_e32 v1, 64, v242
	v_max3_f32 v0, v0, v129, v128
	v_cmp_lt_i32_e32 vcc, v237, v1
	v_max3_f32 v0, v0, v6, v7
	v_max3_f32 v0, v0, v131, v130
	v_cndmask_b32_e32 v2, v220, v237, vcc
	v_lshlrev_b32_e32 v132, 2, v2
	ds_bpermute_b32 v2, v132, v0
	v_cmp_lt_i32_e32 vcc, v236, v1
	s_lshl_b32 s0, s25, 6
	s_lshl_b32 s0, s0, 1
	s_waitcnt lgkmcnt(0)
	v_max_f32_e32 v2, v2, v2
	v_cndmask_b32_e32 v1, v220, v236, vcc
	v_max_f32_e32 v0, v0, v2
	v_lshlrev_b32_e32 v134, 2, v1
	ds_bpermute_b32 v1, v134, v0
	s_xor_b64 s[18:19], s[20:21], -1
	s_mov_b32 s97, 1
	s_mov_b64 s[20:21], 0
	s_and_b64 vcc, exec, s[18:19]
	s_waitcnt lgkmcnt(0)
	v_max_f32_e32 v1, v1, v1
	v_max_f32_e32 v133, v0, v1
	v_sub_f32_e32 v1, v24, v133
	v_mul_f32_e32 v1, 0x3fb8aa3b, v1
	v_exp_f32_e32 v71, v1
	v_sub_f32_e32 v1, v26, v133
	v_mul_f32_e32 v1, 0x3fb8aa3b, v1
	v_exp_f32_e32 v78, v1
	v_sub_f32_e32 v1, v25, v133
	v_mul_f32_e32 v1, 0x3fb8aa3b, v1
	v_exp_f32_e32 v79, v1
	v_sub_f32_e32 v1, v29, v133
	v_mul_f32_e32 v1, 0x3fb8aa3b, v1
	v_exp_f32_e32 v82, v1
	v_sub_f32_e32 v1, v27, v133
	v_mul_f32_e32 v1, 0x3fb8aa3b, v1
	v_exp_f32_e32 v83, v1
	v_sub_f32_e32 v1, v31, v133
	v_mul_f32_e32 v1, 0x3fb8aa3b, v1
	v_exp_f32_e32 v84, v1
	v_sub_f32_e32 v1, v30, v133
	v_mul_f32_e32 v1, 0x3fb8aa3b, v1
	v_exp_f32_e32 v85, v1
	v_sub_f32_e32 v1, v33, v133
	v_mul_f32_e32 v1, 0x3fb8aa3b, v1
	v_exp_f32_e32 v64, v1
	v_sub_f32_e32 v1, v32, v133
	v_mul_f32_e32 v1, 0x3fb8aa3b, v1
	v_exp_f32_e32 v65, v1
	v_sub_f32_e32 v1, v35, v133
	v_mul_f32_e32 v1, 0x3fb8aa3b, v1
	v_exp_f32_e32 v72, v1
	v_sub_f32_e32 v1, v34, v133
	v_mul_f32_e32 v1, 0x3fb8aa3b, v1
	v_exp_f32_e32 v73, v1
	v_sub_f32_e32 v1, v38, v133
	v_mul_f32_e32 v1, 0x3fb8aa3b, v1
	v_exp_f32_e32 v76, v1
	v_sub_f32_e32 v1, v36, v133
	v_mul_f32_e32 v1, 0x3fb8aa3b, v1
	v_exp_f32_e32 v77, v1
	v_sub_f32_e32 v1, v40, v133
	v_mul_f32_e32 v1, 0x3fb8aa3b, v1
	v_exp_f32_e32 v80, v1
	v_sub_f32_e32 v1, v39, v133
	v_mul_f32_e32 v1, 0x3fb8aa3b, v1
	v_exp_f32_e32 v81, v1
	v_sub_f32_e32 v1, v43, v133
	v_mul_f32_e32 v1, 0x3fb8aa3b, v1
	v_exp_f32_e32 v56, v1
	v_sub_f32_e32 v1, v41, v133
	v_mul_f32_e32 v1, 0x3fb8aa3b, v1
	v_exp_f32_e32 v57, v1
	v_sub_f32_e32 v1, v45, v133
	v_mul_f32_e32 v1, 0x3fb8aa3b, v1
	v_exp_f32_e32 v62, v1
	v_sub_f32_e32 v1, v44, v133
	v_mul_f32_e32 v1, 0x3fb8aa3b, v1
	v_exp_f32_e32 v63, v1
	v_sub_f32_e32 v1, v47, v133
	v_mul_f32_e32 v1, 0x3fb8aa3b, v1
	v_exp_f32_e32 v68, v1
	v_sub_f32_e32 v1, v46, v133
	v_mul_f32_e32 v1, 0x3fb8aa3b, v1
	v_exp_f32_e32 v69, v1
	v_sub_f32_e32 v1, v49, v133
	v_mul_f32_e32 v1, 0x3fb8aa3b, v1
	v_exp_f32_e32 v74, v1
	v_sub_f32_e32 v1, v48, v133
	v_mul_f32_e32 v1, 0x3fb8aa3b, v1
	v_exp_f32_e32 v75, v1
	v_sub_f32_e32 v1, v51, v133
	v_mul_f32_e32 v1, 0x3fb8aa3b, v1
	v_exp_f32_e32 v48, v1
	v_sub_f32_e32 v1, v50, v133
	v_mul_f32_e32 v1, 0x3fb8aa3b, v1
	v_exp_f32_e32 v49, v1
	v_sub_f32_e32 v1, v53, v133
	v_mul_f32_e32 v1, 0x3fb8aa3b, v1
	v_exp_f32_e32 v54, v1
	v_sub_f32_e32 v1, v52, v133
	v_mul_f32_e32 v1, 0x3fb8aa3b, v1
	v_exp_f32_e32 v55, v1
	v_sub_f32_e32 v1, v59, v133
	v_mul_f32_e32 v1, 0x3fb8aa3b, v1
	v_exp_f32_e32 v60, v1
	v_sub_f32_e32 v1, v58, v133
	v_mul_f32_e32 v1, 0x3fb8aa3b, v1
	v_exp_f32_e32 v61, v1
	v_sub_f32_e32 v1, v66, v133
	v_mul_f32_e32 v1, 0x3fb8aa3b, v1
	v_exp_f32_e32 v66, v1
	v_sub_f32_e32 v1, v67, v133
	v_sub_f32_e32 v0, v28, v133
	v_mul_f32_e32 v1, 0x3fb8aa3b, v1
	v_mul_f32_e32 v0, 0x3fb8aa3b, v0
	v_exp_f32_e32 v67, v1
	v_sub_f32_e32 v1, v95, v133
	v_exp_f32_e32 v70, v0
	v_mul_f32_e32 v1, 0x3fb8aa3b, v1
	v_exp_f32_e32 v40, v1
	v_sub_f32_e32 v1, v94, v133
	v_mul_f32_e32 v1, 0x3fb8aa3b, v1
	v_exp_f32_e32 v41, v1
	v_sub_f32_e32 v1, v97, v133
	v_add_f32_e32 v0, 0, v70
	v_mul_f32_e32 v1, 0x3fb8aa3b, v1
	v_add_f32_e32 v0, v71, v0
	v_exp_f32_e32 v46, v1
	v_sub_f32_e32 v1, v96, v133
	v_add_f32_e32 v0, v78, v0
	v_mul_f32_e32 v1, 0x3fb8aa3b, v1
	v_add_f32_e32 v0, v79, v0
	v_exp_f32_e32 v47, v1
	v_sub_f32_e32 v1, v99, v133
	v_add_f32_e32 v0, v82, v0
	v_mul_f32_e32 v1, 0x3fb8aa3b, v1
	v_add_f32_e32 v0, v83, v0
	v_exp_f32_e32 v52, v1
	v_sub_f32_e32 v1, v98, v133
	v_add_f32_e32 v0, v84, v0
	v_mul_f32_e32 v1, 0x3fb8aa3b, v1
	v_add_f32_e32 v0, v85, v0
	v_exp_f32_e32 v53, v1
	v_sub_f32_e32 v1, v101, v133
	v_add_f32_e32 v0, v64, v0
	v_mul_f32_e32 v1, 0x3fb8aa3b, v1
	v_add_f32_e32 v0, v65, v0
	v_exp_f32_e32 v58, v1
	v_sub_f32_e32 v1, v100, v133
	v_add_f32_e32 v0, v72, v0
	v_mul_f32_e32 v1, 0x3fb8aa3b, v1
	v_add_f32_e32 v0, v73, v0
	v_exp_f32_e32 v59, v1
	v_sub_f32_e32 v1, v103, v133
	v_add_f32_e32 v0, v76, v0
	v_mul_f32_e32 v1, 0x3fb8aa3b, v1
	v_add_f32_e32 v0, v77, v0
	v_exp_f32_e32 v30, v1
	v_sub_f32_e32 v1, v102, v133
	v_add_f32_e32 v0, v80, v0
	v_mul_f32_e32 v1, 0x3fb8aa3b, v1
	v_add_f32_e32 v0, v81, v0
	v_exp_f32_e32 v31, v1
	v_sub_f32_e32 v1, v105, v133
	v_add_f32_e32 v0, v56, v0
	v_mul_f32_e32 v1, 0x3fb8aa3b, v1
	v_add_f32_e32 v0, v57, v0
	v_exp_f32_e32 v38, v1
	v_sub_f32_e32 v1, v104, v133
	v_add_f32_e32 v0, v62, v0
	v_mul_f32_e32 v1, 0x3fb8aa3b, v1
	v_add_f32_e32 v0, v63, v0
	v_exp_f32_e32 v39, v1
	v_sub_f32_e32 v1, v107, v133
	v_add_f32_e32 v0, v68, v0
	v_mul_f32_e32 v1, 0x3fb8aa3b, v1
	v_add_f32_e32 v0, v69, v0
	v_exp_f32_e32 v44, v1
	v_sub_f32_e32 v1, v106, v133
	v_add_f32_e32 v0, v74, v0
	v_mul_f32_e32 v1, 0x3fb8aa3b, v1
	v_add_f32_e32 v0, v75, v0
	v_exp_f32_e32 v45, v1
	v_sub_f32_e32 v1, v109, v133
	v_add_f32_e32 v0, v48, v0
	v_mul_f32_e32 v1, 0x3fb8aa3b, v1
	v_add_f32_e32 v0, v49, v0
	v_exp_f32_e32 v50, v1
	v_sub_f32_e32 v1, v108, v133
	v_add_f32_e32 v0, v54, v0
	v_mul_f32_e32 v1, 0x3fb8aa3b, v1
	v_add_f32_e32 v0, v55, v0
	v_exp_f32_e32 v51, v1
	v_sub_f32_e32 v1, v111, v133
	v_add_f32_e32 v0, v60, v0
	v_mul_f32_e32 v1, 0x3fb8aa3b, v1
	v_add_f32_e32 v0, v61, v0
	v_exp_f32_e32 v10, v1
	v_sub_f32_e32 v1, v110, v133
	v_add_f32_e32 v0, v66, v0
	v_mul_f32_e32 v1, 0x3fb8aa3b, v1
	v_add_f32_e32 v0, v67, v0
	v_exp_f32_e32 v11, v1
	v_sub_f32_e32 v1, v113, v133
	v_add_f32_e32 v0, v40, v0
	v_mul_f32_e32 v1, 0x3fb8aa3b, v1
	v_add_f32_e32 v0, v41, v0
	v_exp_f32_e32 v28, v1
	v_sub_f32_e32 v1, v112, v133
	v_add_f32_e32 v0, v46, v0
	v_mul_f32_e32 v1, 0x3fb8aa3b, v1
	v_add_f32_e32 v0, v47, v0
	v_exp_f32_e32 v29, v1
	v_sub_f32_e32 v1, v115, v133
	v_add_f32_e32 v0, v52, v0
	v_mul_f32_e32 v1, 0x3fb8aa3b, v1
	v_add_f32_e32 v0, v53, v0
	v_exp_f32_e32 v34, v1
	v_sub_f32_e32 v1, v114, v133
	v_add_f32_e32 v0, v58, v0
	v_mul_f32_e32 v1, 0x3fb8aa3b, v1
	v_add_f32_e32 v0, v59, v0
	v_exp_f32_e32 v35, v1
	v_sub_f32_e32 v1, v117, v133
	v_add_f32_e32 v0, v30, v0
	v_mul_f32_e32 v1, 0x3fb8aa3b, v1
	v_add_f32_e32 v0, v31, v0
	v_exp_f32_e32 v42, v1
	v_sub_f32_e32 v1, v116, v133
	v_add_f32_e32 v0, v38, v0
	v_mul_f32_e32 v1, 0x3fb8aa3b, v1
	v_add_f32_e32 v0, v39, v0
	v_exp_f32_e32 v43, v1
	v_sub_f32_e32 v1, v119, v133
	v_add_f32_e32 v0, v44, v0
	v_mul_f32_e32 v1, 0x3fb8aa3b, v1
	v_add_f32_e32 v0, v45, v0
	v_exp_f32_e32 v4, v1
	v_sub_f32_e32 v1, v118, v133
	v_add_f32_e32 v0, v50, v0
	v_mul_f32_e32 v1, 0x3fb8aa3b, v1
	v_add_f32_e32 v0, v51, v0
	v_exp_f32_e32 v5, v1
	v_sub_f32_e32 v1, v121, v133
	v_add_f32_e32 v0, v10, v0
	v_mul_f32_e32 v1, 0x3fb8aa3b, v1
	v_add_f32_e32 v0, v11, v0
	v_exp_f32_e32 v8, v1
	v_sub_f32_e32 v1, v120, v133
	v_add_f32_e32 v0, v28, v0
	v_mul_f32_e32 v1, 0x3fb8aa3b, v1
	v_add_f32_e32 v0, v29, v0
	v_exp_f32_e32 v9, v1
	v_sub_f32_e32 v1, v123, v133
	v_add_f32_e32 v0, v34, v0
	v_mul_f32_e32 v1, 0x3fb8aa3b, v1
	v_add_f32_e32 v0, v35, v0
	v_exp_f32_e32 v26, v1
	v_sub_f32_e32 v1, v122, v133
	v_add_f32_e32 v0, v42, v0
	v_mul_f32_e32 v1, 0x3fb8aa3b, v1
	v_add_f32_e32 v0, v43, v0
	v_exp_f32_e32 v27, v1
	v_sub_f32_e32 v1, v125, v133
	v_add_f32_e32 v0, v4, v0
	v_mul_f32_e32 v1, 0x3fb8aa3b, v1
	v_add_f32_e32 v0, v5, v0
	v_exp_f32_e32 v32, v1
	v_sub_f32_e32 v1, v124, v133
	v_add_f32_e32 v0, v8, v0
	v_mul_f32_e32 v1, 0x3fb8aa3b, v1
	v_add_f32_e32 v0, v9, v0
	v_exp_f32_e32 v33, v1
	v_add_f32_e32 v0, v26, v0
	v_add_f32_e32 v0, v27, v0
	v_add_f32_e32 v0, v32, v0
	v_add_f32_e32 v1, v33, v0
	v_sub_f32_e32 v0, v127, v133
	v_mul_f32_e32 v0, 0x3fb8aa3b, v0
	v_exp_f32_e32 v0, v0
	v_sub_f32_e32 v6, v6, v133
	v_mul_f32_e32 v6, 0x3fb8aa3b, v6
	v_sub_f32_e32 v7, v7, v133
	v_add_f32_e32 v2, v0, v1
	v_sub_f32_e32 v1, v126, v133
	v_mul_f32_e32 v1, 0x3fb8aa3b, v1
	v_exp_f32_e32 v1, v1
	v_exp_f32_e32 v6, v6
	v_mul_f32_e32 v7, 0x3fb8aa3b, v7
	v_exp_f32_e32 v7, v7
	v_add_f32_e32 v3, v1, v2
	v_sub_f32_e32 v2, v129, v133
	v_mul_f32_e32 v2, 0x3fb8aa3b, v2
	v_exp_f32_e32 v2, v2
	v_sub_f32_e32 v19, v19, v133
	v_mul_f32_e32 v19, 0x3fb8aa3b, v19
	v_exp_f32_e32 v19, v19
	v_add_f32_e32 v24, v2, v3
	v_sub_f32_e32 v3, v128, v133
	v_mul_f32_e32 v3, 0x3fb8aa3b, v3
	v_exp_f32_e32 v3, v3
	ds_read_b128 v[98:101], v15 offset:64768
	ds_read_b128 v[102:105], v86 offset:25088
	ds_read_b128 v[106:109], v86 offset:37632
	v_add_f32_e32 v24, v3, v24
	v_add_f32_e32 v24, v6, v24
	v_add_f32_e32 v25, v7, v24
	v_sub_f32_e32 v24, v131, v133
	v_mul_f32_e32 v24, 0x3fb8aa3b, v24
	v_exp_f32_e32 v24, v24
	s_nop 0
	v_add_f32_e32 v36, v24, v25
	v_sub_f32_e32 v25, v130, v133
	v_mul_f32_e32 v25, 0x3fb8aa3b, v25
	v_exp_f32_e32 v25, v25
	s_nop 0
	v_add_f32_e32 v36, v25, v36
	ds_bpermute_b32 v94, v132, v36
	s_waitcnt lgkmcnt(0)
	v_add_f32_e32 v36, v36, v94
	ds_bpermute_b32 v94, v134, v36
	s_waitcnt lgkmcnt(0)
	v_add_f32_e32 v36, v36, v94
	v_add_f32_e32 v19, v19, v36
	v_rcp_f32_e32 v36, v19
	s_nop 0
	v_pk_mul_f32 v[70:71], v[70:71], v[36:37] op_sel_hi:[1,0]
	v_pk_mul_f32 v[78:79], v[78:79], v[36:37] op_sel_hi:[1,0]
	v_cvt_pk_bf16_f32 v94, v70, v71
	v_cvt_pk_bf16_f32 v95, v78, v79
	v_pk_mul_f32 v[70:71], v[82:83], v[36:37] op_sel_hi:[1,0]
	v_pk_mul_f32 v[78:79], v[84:85], v[36:37] op_sel_hi:[1,0]
	ds_read_b128 v[82:85], v15 offset:52224
	v_pk_mul_f32 v[64:65], v[64:65], v[36:37] op_sel_hi:[1,0]
	v_cvt_pk_bf16_f32 v96, v70, v71
	v_pk_mul_f32 v[72:73], v[72:73], v[36:37] op_sel_hi:[1,0]
	v_cvt_pk_bf16_f32 v70, v64, v65
	v_pk_mul_f32 v[64:65], v[76:77], v[36:37] op_sel_hi:[1,0]
	v_pk_mul_f32 v[76:77], v[80:81], v[36:37] op_sel_hi:[1,0]
	v_cvt_pk_bf16_f32 v97, v78, v79
	v_cvt_pk_bf16_f32 v71, v72, v73
	v_cvt_pk_bf16_f32 v73, v76, v77
	ds_read_b128 v[76:79], v15 offset:52288
	s_waitcnt lgkmcnt(1)
	v_mfma_f32_16x16x32_bf16 v[82:85], v[82:85], v[94:97], 0
	v_cvt_pk_bf16_f32 v72, v64, v65
	v_pk_mul_f32 v[56:57], v[56:57], v[36:37] op_sel_hi:[1,0]
	v_pk_mul_f32 v[64:65], v[62:63], v[36:37] op_sel_hi:[1,0]
	s_waitcnt lgkmcnt(0)
	v_mfma_f32_16x16x32_bf16 v[76:79], v[76:79], v[70:73], v[82:85]
	s_nop 2
	ds_read_b128 v[80:83], v15 offset:64832
	v_cvt_pk_bf16_f32 v62, v56, v57
	v_pk_mul_f32 v[56:57], v[68:69], v[36:37] op_sel_hi:[1,0]
	v_mfma_f32_16x16x32_bf16 v[98:101], v[98:101], v[94:97], 0
	v_mul_f32_e64 v68, v74, v36
	v_mul_f32_e64 v69, v75, v36
	v_cvt_pk_bf16_f32 v63, v64, v65
	v_cvt_pk_bf16_f32 v64, v56, v57
	s_waitcnt lgkmcnt(0)
	v_mfma_f32_16x16x32_bf16 v[80:83], v[80:83], v[70:73], v[98:101]
	v_cvt_pk_bf16_f32 v65, v68, v69
	s_nop 1
	ds_read_b128 v[98:101], v86 offset:25152
	v_pk_mul_f32 v[48:49], v[48:49], v[36:37] op_sel_hi:[1,0]
	v_mfma_f32_16x16x32_bf16 v[102:105], v[102:105], v[94:97], 0
	v_mul_f32_e64 v56, v54, v36
	v_mul_f32_e64 v57, v55, v36
	v_cvt_pk_bf16_f32 v54, v48, v49
	v_pk_mul_f32 v[48:49], v[60:61], v[36:37] op_sel_hi:[1,0]
	s_waitcnt lgkmcnt(0)
	v_mfma_f32_16x16x32_bf16 v[98:101], v[98:101], v[70:73], v[102:105]
	v_mul_f32_e64 v60, v66, v36
	v_mul_f32_e64 v61, v67, v36
	s_nop 0
	ds_read_b128 v[102:105], v86 offset:37696
	v_mfma_f32_16x16x32_bf16 v[94:97], v[106:109], v[94:97], 0
	v_cvt_pk_bf16_f32 v55, v56, v57
	v_cvt_pk_bf16_f32 v56, v48, v49
	v_cvt_pk_bf16_f32 v57, v60, v61
	s_waitcnt lgkmcnt(0)
	v_mfma_f32_16x16x32_bf16 v[70:73], v[102:105], v[70:73], v[94:97]
	v_mul_f32_e64 v40, v40, v36
	v_mul_f32_e64 v41, v41, v36
	s_nop 0
	ds_read_b128 v[94:97], v15 offset:52352
	v_pk_mul_f32 v[48:49], v[46:47], v[36:37] op_sel_hi:[1,0]
	s_waitcnt lgkmcnt(0)
	v_mfma_f32_16x16x32_bf16 v[74:77], v[94:97], v[62:65], v[76:79]
	ds_read_b128 v[94:97], v15 offset:64896
	v_cvt_pk_bf16_f32 v46, v40, v41
	v_pk_mul_f32 v[40:41], v[52:53], v[36:37] op_sel_hi:[1,0]
	s_waitcnt lgkmcnt(0)
	v_mfma_f32_16x16x32_bf16 v[78:81], v[94:97], v[62:65], v[80:83]
	s_nop 2
	ds_read_b128 v[82:85], v86 offset:25216
	ds_read_b128 v[94:97], v86 offset:37760
	s_waitcnt lgkmcnt(1)
	v_mfma_f32_16x16x32_bf16 v[82:85], v[82:85], v[62:65], v[98:101]
	ds_read_b128 v[66:69], v15 offset:52416
	v_pk_mul_f32 v[52:53], v[58:59], v[36:37] op_sel_hi:[1,0]
	v_cvt_pk_bf16_f32 v47, v48, v49
	s_waitcnt lgkmcnt(1)
	v_mfma_f32_16x16x32_bf16 v[62:65], v[94:97], v[62:65], v[70:73]
	v_cvt_pk_bf16_f32 v48, v40, v41
	v_cvt_pk_bf16_f32 v49, v52, v53
	v_pk_mul_f32 v[30:31], v[30:31], v[36:37] op_sel_hi:[1,0]
	ds_read_b128 v[70:73], v15 offset:64960
	s_waitcnt lgkmcnt(1)
	v_mfma_f32_16x16x32_bf16 v[66:69], v[66:69], v[54:57], v[74:77]
	v_mul_f32_e64 v40, v38, v36
	v_mul_f32_e64 v41, v39, v36
	v_cvt_pk_bf16_f32 v38, v30, v31
	ds_read_b128 v[74:77], v86 offset:25280
	s_waitcnt lgkmcnt(1)
	v_mfma_f32_16x16x32_bf16 v[70:73], v[70:73], v[54:57], v[78:81]
	s_nop 2
	ds_read_b128 v[78:81], v86 offset:37824
	ds_read_b128 v[58:61], v15 offset:52480
	s_waitcnt lgkmcnt(2)
	v_mfma_f32_16x16x32_bf16 v[74:77], v[74:77], v[54:57], v[82:85]
	v_mul_f32_e64 v30, v44, v36
	v_mul_f32_e64 v31, v45, v36
	v_pk_mul_f32 v[44:45], v[50:51], v[36:37] op_sel_hi:[1,0]
	v_cvt_pk_bf16_f32 v39, v40, v41
	s_waitcnt lgkmcnt(1)
	v_mfma_f32_16x16x32_bf16 v[54:57], v[78:81], v[54:57], v[62:65]
	v_cvt_pk_bf16_f32 v40, v30, v31
	v_cvt_pk_bf16_f32 v41, v44, v45
	s_nop 0
	ds_read_b128 v[62:65], v15 offset:65024
	s_waitcnt lgkmcnt(1)
	v_mfma_f32_16x16x32_bf16 v[58:61], v[58:61], v[46:49], v[66:69]
	v_mul_f32_e64 v10, v10, v36
	v_mul_f32_e64 v11, v11, v36
	v_pk_mul_f32 v[30:31], v[28:29], v[36:37] op_sel_hi:[1,0]
	v_cvt_pk_bf16_f32 v28, v10, v11
	s_waitcnt lgkmcnt(0)
	v_mfma_f32_16x16x32_bf16 v[62:65], v[62:65], v[46:49], v[70:73]
	ds_read_b128 v[66:69], v86 offset:25344
	s_nop 1
	ds_read_b128 v[70:73], v86 offset:37888
	s_waitcnt lgkmcnt(1)
	v_mfma_f32_16x16x32_bf16 v[66:69], v[66:69], v[46:49], v[74:77]
	ds_read_b128 v[50:53], v15 offset:52544
	v_pk_mul_f32 v[10:11], v[34:35], v[36:37] op_sel_hi:[1,0]
	v_pk_mul_f32 v[34:35], v[42:43], v[36:37] op_sel_hi:[1,0]
	s_waitcnt lgkmcnt(1)
	v_mfma_f32_16x16x32_bf16 v[46:49], v[70:73], v[46:49], v[54:57]
	v_cvt_pk_bf16_f32 v29, v30, v31
	v_cvt_pk_bf16_f32 v30, v10, v11
	v_cvt_pk_bf16_f32 v31, v34, v35
	ds_read_b128 v[54:57], v15 offset:65088
	s_waitcnt lgkmcnt(1)
	v_mfma_f32_16x16x32_bf16 v[50:53], v[50:53], v[38:41], v[58:61]
	v_mul_f32_e64 v4, v4, v36
	v_mul_f32_e64 v5, v5, v36
	v_pk_mul_f32 v[10:11], v[8:9], v[36:37] op_sel_hi:[1,0]
	ds_read_b128 v[58:61], v86 offset:25408
	s_waitcnt lgkmcnt(1)
	v_mfma_f32_16x16x32_bf16 v[54:57], v[54:57], v[38:41], v[62:65]
	s_nop 2
	ds_read_b128 v[62:65], v86 offset:37952
	ds_read_b128 v[42:45], v15 offset:52608
	s_waitcnt lgkmcnt(2)
	v_mfma_f32_16x16x32_bf16 v[58:61], v[58:61], v[38:41], v[66:69]
	v_cvt_pk_bf16_f32 v8, v4, v5
	v_pk_mul_f32 v[4:5], v[26:27], v[36:37] op_sel_hi:[1,0]
	v_pk_mul_f32 v[26:27], v[32:33], v[36:37] op_sel_hi:[1,0]
	s_waitcnt lgkmcnt(1)
	v_mfma_f32_16x16x32_bf16 v[38:41], v[62:65], v[38:41], v[46:49]
	v_cvt_pk_bf16_f32 v9, v10, v11
	v_cvt_pk_bf16_f32 v10, v4, v5
	s_nop 0
	ds_read_b128 v[46:49], v15 offset:65152
	s_waitcnt lgkmcnt(1)
	v_mfma_f32_16x16x32_bf16 v[42:45], v[42:45], v[28:31], v[50:53]
	v_cvt_pk_bf16_f32 v11, v26, v27
	v_pk_mul_f32 v[0:1], v[0:1], v[36:37] op_sel_hi:[1,0]
	v_pk_mul_f32 v[2:3], v[2:3], v[36:37] op_sel_hi:[1,0]
	s_waitcnt lgkmcnt(0)
	v_mfma_f32_16x16x32_bf16 v[46:49], v[46:49], v[28:31], v[54:57]
	ds_read_b128 v[50:53], v86 offset:25472
	s_nop 1
	ds_read_b128 v[54:57], v86 offset:38016
	s_waitcnt lgkmcnt(1)
	v_mfma_f32_16x16x32_bf16 v[50:53], v[50:53], v[28:31], v[58:61]
	ds_read_b128 v[32:35], v15 offset:52672
	v_cvt_pk_bf16_f32 v0, v0, v1
	v_cvt_pk_bf16_f32 v1, v2, v3
	s_waitcnt lgkmcnt(1)
	v_mfma_f32_16x16x32_bf16 v[28:31], v[54:57], v[28:31], v[38:41]
	v_mul_f32_e64 v2, v6, v36
	v_mul_f32_e64 v3, v7, v36
	v_pk_mul_f32 v[4:5], v[24:25], v[36:37] op_sel_hi:[1,0]
	v_cvt_pk_bf16_f32 v2, v2, v3
	ds_read_b128 v[38:41], v15 offset:65216
	s_waitcnt lgkmcnt(1)
	v_mfma_f32_16x16x32_bf16 v[32:35], v[32:35], v[8:11], v[42:45]
	v_cvt_pk_bf16_f32 v3, v4, v5
	s_nop 1
	ds_read_b128 v[42:45], v86 offset:25536
	s_waitcnt lgkmcnt(1)
	v_mfma_f32_16x16x32_bf16 v[38:41], v[38:41], v[8:11], v[46:49]
	s_nop 2
	ds_read_b128 v[46:49], v86 offset:38080
	ds_read_b128 v[4:7], v15 offset:52736
	ds_read_b128 v[24:27], v15 offset:65280
	s_waitcnt lgkmcnt(3)
	v_mfma_f32_16x16x32_bf16 v[42:45], v[42:45], v[8:11], v[50:53]
	s_waitcnt lgkmcnt(2)
	v_mfma_f32_16x16x32_bf16 v[8:11], v[46:49], v[8:11], v[28:31]
	s_nop 2
	ds_read_b128 v[28:31], v86 offset:25600
	s_waitcnt lgkmcnt(2)
	v_mfma_f32_16x16x32_bf16 v[4:7], v[4:7], v[0:3], v[32:35]
	s_nop 2
	ds_read_b128 v[32:35], v86 offset:38144
	s_waitcnt lgkmcnt(2)
	v_mfma_f32_16x16x32_bf16 v[24:27], v[24:27], v[0:3], v[38:41]
	s_nop 1
	v_cvt_pk_bf16_f32 v4, v4, v5
	v_cvt_pk_bf16_f32 v5, v6, v7
	s_waitcnt lgkmcnt(1)
	v_mfma_f32_16x16x32_bf16 v[28:31], v[28:31], v[0:3], v[42:45]
	s_waitcnt lgkmcnt(0)
	v_mfma_f32_16x16x32_bf16 v[0:3], v[32:35], v[0:3], v[8:11]
	v_cvt_pk_bf16_f32 v6, v24, v25
	v_cvt_pk_bf16_f32 v7, v26, v27
	s_nop 0
	v_lshl_add_u64 v[8:9], v[22:23], 0, s[0:1]
	global_store_dwordx4 v[8:9], v[4:7], off
	s_nop 1
	v_cvt_pk_bf16_f32 v4, v28, v29
	v_cvt_pk_bf16_f32 v5, v30, v31
	v_cvt_pk_bf16_f32 v6, v0, v1
	v_cvt_pk_bf16_f32 v7, v2, v3
	global_store_dwordx4 v[8:9], v[4:7], off offset:64
	s_cbranch_vccnz .LBB0_679
.LBB0_701:
	s_or_b32 s25, s97, s24
	s_or_b32 s0, s25, s23
	s_lshl_b64 s[18:19], s[0:1], 2
	s_add_u32 s18, s62, s18
	s_addc_u32 s19, s63, s19
	s_lshl_b32 s0, s25, 7
	v_lshl_add_u64 v[0:1], v[20:21], 0, s[0:1]
	s_cmp_lg_u32 s97, 0
	s_cbranch_scc1 .Lswa_q1
	s_waitcnt vmcnt(0)
	v_mov_b32_e32 v4, v148
	v_mov_b32_e32 v5, v149
	v_mov_b32_e32 v6, v150
	v_mov_b32_e32 v7, v151
	v_mov_b32_e32 v0, v152
	v_mov_b32_e32 v1, v153
	v_mov_b32_e32 v2, v154
	v_mov_b32_e32 v3, v155
	s_branch .Lswa_qd
.Lswa_q1:
	v_mov_b32_e32 v4, v156
	v_mov_b32_e32 v5, v157
	v_mov_b32_e32 v6, v158
	v_mov_b32_e32 v7, v159
	v_mov_b32_e32 v0, v160
	v_mov_b32_e32 v1, v161
	v_mov_b32_e32 v2, v162
	v_mov_b32_e32 v3, v163
.Lswa_qd:
	global_load_dword v19, v193, s[18:19]
	ds_read2_b64 v[8:11], v14 offset1:1
	ds_read2_b64 v[24:27], v14 offset0:8 offset1:9
	s_mul_i32 s0, s97, 0x404
	s_add_i32 s0, s0, 0x19000
	v_lshl_add_u32 v42, v88, 2, s0
	v_mov_b32_e32 v28, 0xf149f2ca
	s_waitcnt lgkmcnt(1)
	v_mfma_f32_16x16x32_bf16 v[8:11], v[8:11], v[4:7], 0
	s_waitcnt lgkmcnt(0)
	v_mfma_f32_16x16x32_bf16 v[8:11], v[24:27], v[0:3], v[8:11]
	v_mov_b32_e32 v24, 0xf149f2ca
	s_and_saveexec_b64 s[18:19], s[66:67]
	s_cbranch_execz .LBB0_703
	ds_read_b32 v25, v42 offset:512
	s_waitcnt lgkmcnt(0)
	s_nop 2
	v_add_f32_e32 v28, v8, v25

.LBB0_991:
	v_or_b32_e32 v68, 0x10000, v155
	v_add_u32_e32 v72, 0x10400, v155
	v_add_u32_e32 v150, 0x10800, v155
	v_add_u32_e32 v156, 0x10c00, v155
	ds_read_b128 v[68:71], v68
	ds_read_b128 v[72:75], v72
	ds_read_b128 v[150:153], v150
	ds_read_b128 v[156:159], v156
	s_add_u32 s22, s20, 0xfffc0080
	s_addc_u32 s23, s21, -1
	s_cmp_eq_u32 s67, 12
	s_cselect_b32 s25, s0, s23
	s_cselect_b32 s24, s7, s22
	s_cselect_b32 s23, s9, s66
	s_cselect_b32 s22, s64, s65
	v_lshl_add_u64 v[206:207], s[20:21], 0, v[146:147]
	s_add_i32 m0, s5, 0xc000
	ds_read_b128 v[160:163], v154
	ds_read_b128 v[164:167], v154 offset:1024
	ds_read_b128 v[168:171], v154 offset:2048
	ds_read_b128 v[172:175], v154 offset:3072
	ds_read_b128 v[176:179], v154 offset:4096
	ds_read_b128 v[180:183], v154 offset:5120
	ds_read_b128 v[184:187], v154 offset:6144
	ds_read_b128 v[188:191], v154 offset:7168
	global_load_lds_dwordx4 v[206:207], off
	v_lshl_add_u64 v[206:207], s[20:21], 0, v[148:149]
	s_add_i32 m0, s5, 0xe000
	s_nop 0
	global_load_lds_dwordx4 v[206:207], off
	s_waitcnt lgkmcnt(8)
	s_barrier
	s_waitcnt lgkmcnt(0)
	s_setprio 1
	s_waitcnt lgkmcnt(0)
	v_mfma_f32_16x16x32_bf16 v[76:79], v[68:71], v[160:163], v[76:79]
	v_mfma_f32_16x16x32_bf16 v[64:67], v[150:153], v[160:163], v[64:67]
	v_mfma_f32_16x16x32_bf16 v[124:127], v[68:71], v[168:171], v[124:127]
	v_mfma_f32_16x16x32_bf16 v[120:123], v[150:153], v[168:171], v[120:123]
	v_mfma_f32_16x16x32_bf16 v[108:111], v[68:71], v[176:179], v[108:111]
	v_mfma_f32_16x16x32_bf16 v[104:107], v[150:153], v[176:179], v[104:107]
	v_mfma_f32_16x16x32_bf16 v[92:95], v[68:71], v[184:187], v[92:95]
	v_mfma_f32_16x16x32_bf16 v[88:91], v[150:153], v[184:187], v[88:91]
	v_mfma_f32_16x16x32_bf16 v[76:79], v[72:75], v[164:167], v[76:79]
	v_mfma_f32_16x16x32_bf16 v[64:67], v[156:159], v[164:167], v[64:67]
	v_mfma_f32_16x16x32_bf16 v[124:127], v[72:75], v[172:175], v[124:127]
	v_mfma_f32_16x16x32_bf16 v[120:123], v[156:159], v[172:175], v[120:123]
	v_mfma_f32_16x16x32_bf16 v[108:111], v[72:75], v[180:183], v[108:111]
	v_mfma_f32_16x16x32_bf16 v[104:107], v[156:159], v[180:183], v[104:107]
	v_mfma_f32_16x16x32_bf16 v[92:95], v[72:75], v[188:191], v[92:95]
	v_mfma_f32_16x16x32_bf16 v[88:91], v[156:159], v[188:191], v[88:91]
	s_setprio 0
	s_barrier
	v_or_b32_e32 v201, 0x14000, v155
	v_add_u32_e32 v210, 0x14400, v155
	ds_read_b128 v[206:209], v201
	ds_read_b128 v[210:213], v210
	v_add_u32_e32 v201, 0x14800, v155
	v_add_u32_e32 v218, 0x14c00, v155
	s_mov_b32 m0, s19
	ds_read_b128 v[214:217], v201
	ds_read_b128 v[244:247], v218
	v_lshl_add_u64 v[218:219], s[22:23], 0, v[140:141]
	global_load_lds_dwordx4 v[218:219], off
	v_lshl_add_u64 v[248:249], s[22:23], 0, v[136:137]
	s_mov_b32 m0, s31
	s_nop 0
	global_load_lds_dwordx4 v[248:249], off
	s_barrier
	s_waitcnt lgkmcnt(0)
	s_setprio 1
	s_waitcnt lgkmcnt(0)
	v_mfma_f32_16x16x32_bf16 v[132:135], v[206:209], v[160:163], v[132:135]
	v_mfma_f32_16x16x32_bf16 v[128:131], v[214:217], v[160:163], v[128:131]
	v_mfma_f32_16x16x32_bf16 v[116:119], v[206:209], v[168:171], v[116:119]
	v_mfma_f32_16x16x32_bf16 v[112:115], v[214:217], v[168:171], v[112:115]
	v_mfma_f32_16x16x32_bf16 v[100:103], v[206:209], v[176:179], v[100:103]
	v_mfma_f32_16x16x32_bf16 v[96:99], v[214:217], v[176:179], v[96:99]
	v_mfma_f32_16x16x32_bf16 v[84:87], v[206:209], v[184:187], v[84:87]
	v_mfma_f32_16x16x32_bf16 v[80:83], v[214:217], v[184:187], v[80:83]
	v_mfma_f32_16x16x32_bf16 v[132:135], v[210:213], v[164:167], v[132:135]
	v_mfma_f32_16x16x32_bf16 v[128:131], v[244:247], v[164:167], v[128:131]
	v_mfma_f32_16x16x32_bf16 v[116:119], v[210:213], v[172:175], v[116:119]
	v_mfma_f32_16x16x32_bf16 v[112:115], v[244:247], v[172:175], v[112:115]
	v_mfma_f32_16x16x32_bf16 v[100:103], v[210:213], v[180:183], v[100:103]
	v_mfma_f32_16x16x32_bf16 v[96:99], v[244:247], v[180:183], v[96:99]
	v_mfma_f32_16x16x32_bf16 v[84:87], v[210:213], v[188:191], v[84:87]
	v_mfma_f32_16x16x32_bf16 v[80:83], v[244:247], v[188:191], v[80:83]
	s_setprio 0
	s_mov_b32 m0, s5
	v_lshl_add_u64 v[250:251], s[24:25], 0, v[142:143]
	s_barrier
	ds_read_b128 v[160:163], v154 offset:16384
	ds_read_b128 v[164:167], v154 offset:17408
	ds_read_b128 v[168:171], v154 offset:18432
	ds_read_b128 v[172:175], v154 offset:19456
	ds_read_b128 v[176:179], v154 offset:20480
	ds_read_b128 v[180:183], v154 offset:21504
	ds_read_b128 v[184:187], v154 offset:22528
	ds_read_b128 v[188:191], v154 offset:23552
	global_load_lds_dwordx4 v[250:251], off
	v_lshl_add_u64 v[232:233], s[24:25], 0, v[138:139]
	s_mov_b32 m0, s34
	s_nop 0
	global_load_lds_dwordx4 v[232:233], off
	s_barrier
	s_waitcnt lgkmcnt(0)
	s_setprio 1
	s_waitcnt lgkmcnt(0)
	v_mfma_f32_16x16x32_bf16 v[60:63], v[68:71], v[160:163], v[60:63]
	v_mfma_f32_16x16x32_bf16 v[56:59], v[150:153], v[160:163], v[56:59]
	v_mfma_f32_16x16x32_bf16 v[44:47], v[68:71], v[168:171], v[44:47]
	v_mfma_f32_16x16x32_bf16 v[40:43], v[150:153], v[168:171], v[40:43]
	v_mfma_f32_16x16x32_bf16 v[28:31], v[68:71], v[176:179], v[28:31]
	v_mfma_f32_16x16x32_bf16 v[24:27], v[150:153], v[176:179], v[24:27]
	v_mfma_f32_16x16x32_bf16 v[12:15], v[68:71], v[184:187], v[12:15]
	v_mfma_f32_16x16x32_bf16 v[8:11], v[150:153], v[184:187], v[8:11]
	v_mfma_f32_16x16x32_bf16 v[60:63], v[72:75], v[164:167], v[60:63]
	v_mfma_f32_16x16x32_bf16 v[56:59], v[156:159], v[164:167], v[56:59]
	v_mfma_f32_16x16x32_bf16 v[44:47], v[72:75], v[172:175], v[44:47]
	v_mfma_f32_16x16x32_bf16 v[40:43], v[156:159], v[172:175], v[40:43]
	v_mfma_f32_16x16x32_bf16 v[28:31], v[72:75], v[180:183], v[28:31]
	v_mfma_f32_16x16x32_bf16 v[24:27], v[156:159], v[180:183], v[24:27]
	v_mfma_f32_16x16x32_bf16 v[12:15], v[72:75], v[188:191], v[12:15]
	v_mfma_f32_16x16x32_bf16 v[8:11], v[156:159], v[188:191], v[8:11]
	s_setprio 0
	s_barrier
	s_add_u32 s68, s22, 0x40000
	s_addc_u32 s69, s23, 0
	s_mov_b32 m0, s35
	v_lshl_add_u64 v[68:69], s[68:69], 0, v[140:141]
	global_load_lds_dwordx4 v[68:69], off
	v_lshl_add_u64 v[68:69], s[68:69], 0, v[136:137]
	s_mov_b32 m0, s36
	s_nop 0
	global_load_lds_dwordx4 v[68:69], off
	s_waitcnt vmcnt(6)
	s_barrier
	s_setprio 1
	v_mfma_f32_16x16x32_bf16 v[52:55], v[206:209], v[160:163], v[52:55]
	v_mfma_f32_16x16x32_bf16 v[48:51], v[214:217], v[160:163], v[48:51]
	v_mfma_f32_16x16x32_bf16 v[36:39], v[206:209], v[168:171], v[36:39]
	v_mfma_f32_16x16x32_bf16 v[32:35], v[214:217], v[168:171], v[32:35]
	v_mfma_f32_16x16x32_bf16 v[20:23], v[206:209], v[176:179], v[20:23]
	v_mfma_f32_16x16x32_bf16 v[16:19], v[214:217], v[176:179], v[16:19]
	v_mfma_f32_16x16x32_bf16 v[4:7], v[206:209], v[184:187], v[4:7]
	v_mfma_f32_16x16x32_bf16 v[0:3], v[214:217], v[184:187], v[0:3]
	v_mfma_f32_16x16x32_bf16 v[52:55], v[210:213], v[164:167], v[52:55]
	v_mfma_f32_16x16x32_bf16 v[48:51], v[244:247], v[164:167], v[48:51]
	v_mfma_f32_16x16x32_bf16 v[36:39], v[210:213], v[172:175], v[36:39]
	v_mfma_f32_16x16x32_bf16 v[32:35], v[244:247], v[172:175], v[32:35]
	v_mfma_f32_16x16x32_bf16 v[20:23], v[210:213], v[180:183], v[20:23]
	v_mfma_f32_16x16x32_bf16 v[16:19], v[244:247], v[180:183], v[16:19]
	v_mfma_f32_16x16x32_bf16 v[4:7], v[210:213], v[188:191], v[4:7]
	v_mfma_f32_16x16x32_bf16 v[0:3], v[244:247], v[188:191], v[0:3]
	s_setprio 0
	v_or_b32_e32 v68, 0x18000, v155
	v_add_u32_e32 v72, 0x18400, v155
	v_add_u32_e32 v150, 0x18800, v155
	v_add_u32_e32 v156, 0x18c00, v155
	s_barrier
	ds_read_b128 v[68:71], v68
	ds_read_b128 v[72:75], v72
	ds_read_b128 v[150:153], v150
	ds_read_b128 v[156:159], v156
	s_add_u32 s24, s24, 0x40000
	s_addc_u32 s25, s25, 0
	s_mov_b32 m0, s37
	v_lshl_add_u64 v[206:207], s[24:25], 0, v[142:143]
	ds_read_b128 v[160:163], v154 offset:32768
	ds_read_b128 v[164:167], v154 offset:33792
	ds_read_b128 v[168:171], v154 offset:34816
	ds_read_b128 v[172:175], v154 offset:35840
	ds_read_b128 v[176:179], v154 offset:36864
	ds_read_b128 v[180:183], v154 offset:37888
	ds_read_b128 v[184:187], v154 offset:38912
	ds_read_b128 v[188:191], v154 offset:39936
	global_load_lds_dwordx4 v[206:207], off
	v_lshl_add_u64 v[206:207], s[24:25], 0, v[138:139]
	s_mov_b32 m0, s38
	s_nop 0
	global_load_lds_dwordx4 v[206:207], off
	s_waitcnt lgkmcnt(8)
	s_barrier
	s_waitcnt lgkmcnt(0)
	s_setprio 1
	s_waitcnt lgkmcnt(0)
	v_mfma_f32_16x16x32_bf16 v[76:79], v[68:71], v[160:163], v[76:79]
	v_mfma_f32_16x16x32_bf16 v[64:67], v[150:153], v[160:163], v[64:67]
	v_mfma_f32_16x16x32_bf16 v[124:127], v[68:71], v[168:171], v[124:127]
	v_mfma_f32_16x16x32_bf16 v[120:123], v[150:153], v[168:171], v[120:123]
	v_mfma_f32_16x16x32_bf16 v[108:111], v[68:71], v[176:179], v[108:111]
	v_mfma_f32_16x16x32_bf16 v[104:107], v[150:153], v[176:179], v[104:107]
	v_mfma_f32_16x16x32_bf16 v[92:95], v[68:71], v[184:187], v[92:95]
	v_mfma_f32_16x16x32_bf16 v[88:91], v[150:153], v[184:187], v[88:91]
	v_mfma_f32_16x16x32_bf16 v[76:79], v[72:75], v[164:167], v[76:79]
	v_mfma_f32_16x16x32_bf16 v[64:67], v[156:159], v[164:167], v[64:67]
	v_mfma_f32_16x16x32_bf16 v[124:127], v[72:75], v[172:175], v[124:127]
	v_mfma_f32_16x16x32_bf16 v[120:123], v[156:159], v[172:175], v[120:123]
	v_mfma_f32_16x16x32_bf16 v[108:111], v[72:75], v[180:183], v[108:111]
	v_mfma_f32_16x16x32_bf16 v[104:107], v[156:159], v[180:183], v[104:107]
	v_mfma_f32_16x16x32_bf16 v[92:95], v[72:75], v[188:191], v[92:95]
	v_mfma_f32_16x16x32_bf16 v[88:91], v[156:159], v[188:191], v[88:91]
	s_setprio 0
	s_barrier
	v_or_b32_e32 v201, 0x1c000, v155
	v_add_u32_e32 v210, 0x1c400, v155
	s_mov_b32 m0, s39
	ds_read_b128 v[206:209], v201
	ds_read_b128 v[210:213], v210
	v_add_u32_e32 v201, 0x1c800, v155
	v_lshl_add_u64 v[218:219], v[218:219], 0, s[94:95]
	v_add_u32_e32 v228, 0x1cc00, v155
	ds_read_b128 v[214:217], v201
	ds_read_b128 v[244:247], v228
	global_load_lds_dwordx4 v[218:219], off
	v_lshl_add_u64 v[218:219], v[248:249], 0, s[94:95]
	s_mov_b32 m0, s40
	s_nop 0
	global_load_lds_dwordx4 v[218:219], off
	s_barrier
	s_waitcnt lgkmcnt(0)
	s_setprio 1
	s_waitcnt lgkmcnt(0)
	v_mfma_f32_16x16x32_bf16 v[132:135], v[206:209], v[160:163], v[132:135]
	v_mfma_f32_16x16x32_bf16 v[128:131], v[214:217], v[160:163], v[128:131]
	v_mfma_f32_16x16x32_bf16 v[116:119], v[206:209], v[168:171], v[116:119]
	v_mfma_f32_16x16x32_bf16 v[112:115], v[214:217], v[168:171], v[112:115]
	v_mfma_f32_16x16x32_bf16 v[100:103], v[206:209], v[176:179], v[100:103]
	v_mfma_f32_16x16x32_bf16 v[96:99], v[214:217], v[176:179], v[96:99]
	v_mfma_f32_16x16x32_bf16 v[84:87], v[206:209], v[184:187], v[84:87]
	v_mfma_f32_16x16x32_bf16 v[80:83], v[214:217], v[184:187], v[80:83]
	v_mfma_f32_16x16x32_bf16 v[132:135], v[210:213], v[164:167], v[132:135]
	v_mfma_f32_16x16x32_bf16 v[128:131], v[244:247], v[164:167], v[128:131]
	v_mfma_f32_16x16x32_bf16 v[116:119], v[210:213], v[172:175], v[116:119]
	v_mfma_f32_16x16x32_bf16 v[112:115], v[244:247], v[172:175], v[112:115]
	v_mfma_f32_16x16x32_bf16 v[100:103], v[210:213], v[180:183], v[100:103]
	v_mfma_f32_16x16x32_bf16 v[96:99], v[244:247], v[180:183], v[96:99]
	v_mfma_f32_16x16x32_bf16 v[84:87], v[210:213], v[188:191], v[84:87]
	v_mfma_f32_16x16x32_bf16 v[80:83], v[244:247], v[188:191], v[80:83]
	s_setprio 0
	s_mov_b32 m0, s41
	v_lshl_add_u64 v[218:219], v[250:251], 0, s[94:95]
	s_barrier
	ds_read_b128 v[160:163], v154 offset:49152
	ds_read_b128 v[164:167], v154 offset:50176
	ds_read_b128 v[168:171], v154 offset:51200
	ds_read_b128 v[172:175], v154 offset:52224
	ds_read_b128 v[176:179], v154 offset:53248
	ds_read_b128 v[180:183], v154 offset:54272
	ds_read_b128 v[184:187], v154 offset:55296
	ds_read_b128 v[188:191], v154 offset:56320
	global_load_lds_dwordx4 v[218:219], off
	v_lshl_add_u64 v[218:219], v[232:233], 0, s[94:95]
	s_mov_b32 m0, s42
	s_nop 0
	global_load_lds_dwordx4 v[218:219], off
	s_barrier
	s_waitcnt lgkmcnt(0)
	s_setprio 1
	s_waitcnt lgkmcnt(0)
	v_mfma_f32_16x16x32_bf16 v[60:63], v[68:71], v[160:163], v[60:63]
	v_mfma_f32_16x16x32_bf16 v[56:59], v[150:153], v[160:163], v[56:59]
	v_mfma_f32_16x16x32_bf16 v[44:47], v[68:71], v[168:171], v[44:47]
	v_mfma_f32_16x16x32_bf16 v[40:43], v[150:153], v[168:171], v[40:43]
	v_mfma_f32_16x16x32_bf16 v[28:31], v[68:71], v[176:179], v[28:31]
	v_mfma_f32_16x16x32_bf16 v[24:27], v[150:153], v[176:179], v[24:27]
	v_mfma_f32_16x16x32_bf16 v[12:15], v[68:71], v[184:187], v[12:15]
	v_mfma_f32_16x16x32_bf16 v[8:11], v[150:153], v[184:187], v[8:11]
	v_mfma_f32_16x16x32_bf16 v[60:63], v[72:75], v[164:167], v[60:63]
	v_mfma_f32_16x16x32_bf16 v[56:59], v[156:159], v[164:167], v[56:59]
	v_mfma_f32_16x16x32_bf16 v[44:47], v[72:75], v[172:175], v[44:47]
	v_mfma_f32_16x16x32_bf16 v[40:43], v[156:159], v[172:175], v[40:43]
	v_mfma_f32_16x16x32_bf16 v[28:31], v[72:75], v[180:183], v[28:31]
	v_mfma_f32_16x16x32_bf16 v[24:27], v[156:159], v[180:183], v[24:27]
	v_mfma_f32_16x16x32_bf16 v[12:15], v[72:75], v[188:191], v[12:15]
	v_mfma_f32_16x16x32_bf16 v[8:11], v[156:159], v[188:191], v[8:11]
	s_setprio 0
	s_barrier
	s_add_u32 s22, s22, 0x40080
	s_addc_u32 s23, s23, 0
	s_mov_b32 m0, s43
	v_lshl_add_u64 v[68:69], s[22:23], 0, v[140:141]
	global_load_lds_dwordx4 v[68:69], off
	v_lshl_add_u64 v[68:69], s[22:23], 0, v[136:137]
	s_mov_b32 m0, s44
	s_nop 0
	global_load_lds_dwordx4 v[68:69], off
	s_waitcnt vmcnt(6)
	s_barrier
	s_setprio 1
	v_mfma_f32_16x16x32_bf16 v[52:55], v[206:209], v[160:163], v[52:55]
	v_mfma_f32_16x16x32_bf16 v[48:51], v[214:217], v[160:163], v[48:51]
	v_mfma_f32_16x16x32_bf16 v[36:39], v[206:209], v[168:171], v[36:39]
	v_mfma_f32_16x16x32_bf16 v[32:35], v[214:217], v[168:171], v[32:35]
	v_mfma_f32_16x16x32_bf16 v[20:23], v[206:209], v[176:179], v[20:23]
	v_mfma_f32_16x16x32_bf16 v[16:19], v[214:217], v[176:179], v[16:19]
	v_mfma_f32_16x16x32_bf16 v[4:7], v[206:209], v[184:187], v[4:7]
	v_mfma_f32_16x16x32_bf16 v[0:3], v[214:217], v[184:187], v[0:3]
	v_mfma_f32_16x16x32_bf16 v[52:55], v[210:213], v[164:167], v[52:55]
	v_mfma_f32_16x16x32_bf16 v[48:51], v[244:247], v[164:167], v[48:51]
	v_mfma_f32_16x16x32_bf16 v[36:39], v[210:213], v[172:175], v[36:39]
	v_mfma_f32_16x16x32_bf16 v[32:35], v[244:247], v[172:175], v[32:35]
	v_mfma_f32_16x16x32_bf16 v[20:23], v[210:213], v[180:183], v[20:23]
	v_mfma_f32_16x16x32_bf16 v[16:19], v[244:247], v[180:183], v[16:19]
	v_mfma_f32_16x16x32_bf16 v[4:7], v[210:213], v[188:191], v[4:7]
	v_mfma_f32_16x16x32_bf16 v[0:3], v[244:247], v[188:191], v[0:3]
	s_setprio 0
	s_add_i32 s67, s67, 2
	s_add_u32 s20, s20, 0x100
	s_addc_u32 s21, s21, 0
	s_add_u32 s65, s65, 0x100
	s_addc_u32 s66, s66, 0
	s_cmp_gt_u32 s67, 13
	s_barrier
	s_cbranch_scc0 .LBB0_991
	s_lshl_b32 s20, s18, 8
	v_readlane_b32 s48, v253, 6
	s_add_i32 s0, s20, 0xffff0000
	v_readlane_b32 s50, v253, 8
	v_readlane_b32 s51, v253, 9
	s_lshr_b32 s7, s0, 13
	s_ashr_i32 s21, s20, 31
	v_readlane_b32 s49, v253, 7
	s_mov_b64 s[66:67], s[50:51]
	s_add_i32 s7, s7, 16
	s_ashr_i32 s9, s18, 4
	s_lshl_b64 s[22:23], s[20:21], 12
	s_mov_b64 s[64:65], s[48:49]
	s_add_u32 s24, s64, s22
	s_addc_u32 s25, s65, s23
	s_lshl_b64 s[22:23], s[0:1], 12
	s_add_u32 s0, s66, s22
	s_addc_u32 s22, s67, s23
	s_cmpk_lt_i32 s18, 0x100
	s_cselect_b32 s7, s9, s7
	s_mul_hi_i32 s9, s7, 0x6000
	s_mulk_i32 s7, 0x6000
	s_cselect_b32 s18, s25, s22
	v_readlane_b32 s22, v253, 1
	s_cselect_b32 s0, s24, s0
	v_readlane_b32 s23, v253, 2
	s_add_u32 s7, s22, s7
	s_addc_u32 s9, s23, s9
	s_lshl_b32 s22, s47, 8
	s_ashr_i32 s23, s22, 31
	s_lshl_b64 s[24:25], s[22:23], 2
	s_add_u32 s7, s7, s24
	s_addc_u32 s9, s9, s25
	s_add_u32 s24, s7, s46
	s_addc_u32 s25, s9, 0
	v_lshl_add_u64 v[68:69], s[24:25], 0, v[192:193]
	s_mov_b64 s[24:25], 0x4402000
	v_lshl_add_u64 v[164:165], v[68:69], 0, s[24:25]
	v_mov_b32_e32 v70, s0
	s_lshl_b64 s[20:21], s[20:21], 11
	v_readlane_b32 s24, v253, 48
	s_mov_b32 s0, 0x4402000
	v_readlane_b32 s25, v253, 49
	s_add_u32 s20, s24, s20
	v_add_co_u32_e32 v68, vcc, s0, v68
	v_mov_b32_e32 v71, s18
	s_addc_u32 s21, s25, s21
	v_lshl_add_u64 v[72:73], v[144:145], 0, s[22:23]
	v_addc_co_u32_e32 v69, vcc, 0, v69, vcc
	v_lshl_add_u64 v[150:151], v[72:73], 1, s[20:21]
	v_lshl_add_u64 v[152:153], v[72:73], 2, v[70:71]
	global_load_dwordx4 v[72:75], v[68:69], off
	s_nop 0
	global_load_dwordx4 v[68:71], v[164:165], off offset:16
	s_mov_b32 s98, 0x0
	s_mov_b32 s99, 0
	v_lshl_add_u64 v[244:245], v[152:153], 0, s[98:99]
	global_load_dwordx4 v[172:175], v[244:245], off offset:16
	global_load_dwordx4 v[176:179], v[244:245], off
	global_load_dwordx4 v[180:183], v[244:245], off offset:528
	global_load_dwordx4 v[184:187], v[244:245], off offset:512
	s_mov_b32 s98, 0x10000
	s_mov_b32 s99, 0
	v_lshl_add_u64 v[244:245], v[152:153], 0, s[98:99]
	global_load_dwordx4 v[188:191], v[244:245], off
	global_load_dwordx4 v[206:209], v[244:245], off offset:16
	global_load_dwordx4 v[210:213], v[244:245], off offset:512
	global_load_dwordx4 v[214:217], v[244:245], off offset:528
	s_waitcnt vmcnt(7)
	v_mov_b32_e32 v156, v172
	v_mov_b32_e32 v157, v173
	v_mov_b32_e32 v158, v174
	v_mov_b32_e32 v159, v175
	s_mov_b32 s98, 0x20000
	s_mov_b32 s99, 0
	v_lshl_add_u64 v[244:245], v[152:153], 0, s[98:99]
	global_load_dwordx4 v[172:175], v[244:245], off
	s_waitcnt vmcnt(7)
	v_mov_b32_e32 v160, v176
	v_mov_b32_e32 v161, v177
	v_mov_b32_e32 v162, v178
	v_mov_b32_e32 v163, v179
	global_load_dwordx4 v[176:179], v[244:245], off offset:16
	s_mov_b32 s7, 0x10000
	s_mov_b64 s[20:21], 0x10000
	v_lshl_add_u64 v[168:169], v[152:153], 0, s[20:21]
	s_mov_b64 s[20:21], 0x10200
	v_lshl_add_u64 v[170:171], v[152:153], 0, s[20:21]
	s_mov_b32 s0, 0x8000
	s_mov_b64 s[20:21], 0x20000
	v_readlane_b32 s52, v253, 10
	v_readlane_b32 s53, v253, 11
	v_readlane_b32 s54, v253, 12
	v_readlane_b32 s55, v253, 13
	v_readlane_b32 s56, v253, 14
	v_readlane_b32 s57, v253, 15
	v_readlane_b32 s58, v253, 16
	v_readlane_b32 s59, v253, 17
	v_readlane_b32 s60, v253, 18
	v_readlane_b32 s61, v253, 19
	v_readlane_b32 s62, v253, 20
	v_readlane_b32 s63, v253, 21
	v_readlane_b32 s48, v253, 30
	s_mov_b32 s47, s6
	s_mov_b32 s18, s8
	s_mov_b64 s[22:23], s[16:17]
	v_readlane_b32 s49, v253, 31
	v_readlane_b32 s50, v253, 32
	v_readlane_b32 s51, v253, 33
	v_readlane_b32 s52, v253, 34
	v_readlane_b32 s53, v253, 35
	v_readlane_b32 s54, v253, 36
	v_readlane_b32 s55, v253, 37
	v_readlane_b32 s56, v253, 38
	v_readlane_b32 s57, v253, 39
	v_readlane_b32 s58, v253, 40
	v_readlane_b32 s59, v253, 41
	v_readlane_b32 s60, v253, 42
	v_readlane_b32 s61, v253, 43
	v_readlane_b32 s62, v253, 44
	v_readlane_b32 s63, v253, 45
	s_waitcnt vmcnt(10)
	v_pk_fma_f32 v[64:65], v[64:65], v[68:69], v[156:157]
	v_pk_fma_f32 v[76:77], v[76:77], v[72:73], v[160:161]
	s_nop 0
	v_cvt_pk_bf16_f32 v160, v76, v77
	v_pk_fma_f32 v[76:77], v[78:79], v[74:75], v[162:163]
	v_cvt_pk_bf16_f32 v162, v64, v65
	v_pk_fma_f32 v[64:65], v[66:67], v[70:71], v[158:159]
	v_cvt_pk_bf16_f32 v161, v76, v77
	v_cvt_pk_bf16_f32 v163, v64, v65
	global_load_dwordx4 v[64:67], v[164:165], off offset:528
	global_load_dwordx4 v[76:79], v[164:165], off offset:512
	s_waitcnt vmcnt(9)
	v_mov_b32_e32 v156, v180
	v_mov_b32_e32 v157, v181
	v_mov_b32_e32 v158, v182
	v_mov_b32_e32 v159, v183
	global_load_dwordx4 v[180:183], v[244:245], off offset:512
	s_nop 0
	s_waitcnt vmcnt(9)
	v_mov_b32_e32 v164, v184
	v_mov_b32_e32 v165, v185
	v_mov_b32_e32 v166, v186
	v_mov_b32_e32 v167, v187
	global_load_dwordx4 v[184:187], v[244:245], off offset:528
	s_waitcnt vmcnt(2)
	v_pk_fma_f32 v[128:129], v[128:129], v[64:65], v[156:157]
	v_pk_fma_f32 v[132:133], v[132:133], v[76:77], v[164:165]
	v_pk_fma_f32 v[134:135], v[134:135], v[78:79], v[166:167]
	v_add_co_u32_e32 v164, vcc, s7, v152
	v_cvt_pk_bf16_f32 v132, v132, v133
	v_cvt_pk_bf16_f32 v133, v134, v135
	v_cvt_pk_bf16_f32 v134, v128, v129
	v_pk_fma_f32 v[128:129], v[130:131], v[66:67], v[158:159]
	v_addc_co_u32_e32 v165, vcc, 0, v153, vcc
	v_cvt_pk_bf16_f32 v135, v128, v129
	s_waitcnt vmcnt(9)
	v_mov_b32_e32 v128, v188
	v_mov_b32_e32 v129, v189
	v_mov_b32_e32 v130, v190
	v_mov_b32_e32 v131, v191
	s_mov_b32 s98, 0x30000
	s_mov_b32 s99, 0
	v_lshl_add_u64 v[244:245], v[152:153], 0, s[98:99]
	global_load_dwordx4 v[188:191], v[244:245], off
	s_waitcnt vmcnt(9)
	v_mov_b32_e32 v156, v206
	v_mov_b32_e32 v157, v207
	v_mov_b32_e32 v158, v208
	v_mov_b32_e32 v159, v209
	global_load_dwordx4 v[206:209], v[244:245], off offset:16
	s_waitcnt vmcnt(4)
	v_pk_fma_f32 v[124:125], v[124:125], v[72:73], v[128:129]
	v_pk_fma_f32 v[126:127], v[126:127], v[74:75], v[130:131]
	v_pk_fma_f32 v[120:121], v[120:121], v[68:69], v[156:157]
	v_cvt_pk_bf16_f32 v124, v124, v125
	v_cvt_pk_bf16_f32 v125, v126, v127
	v_cvt_pk_bf16_f32 v126, v120, v121
	v_pk_fma_f32 v[120:121], v[122:123], v[70:71], v[158:159]
	s_nop 0
	v_cvt_pk_bf16_f32 v127, v120, v121
	s_waitcnt vmcnt(9)
	v_mov_b32_e32 v120, v210
	v_mov_b32_e32 v121, v211
	v_mov_b32_e32 v122, v212
	v_mov_b32_e32 v123, v213
	global_load_dwordx4 v[210:213], v[244:245], off offset:512
	s_waitcnt vmcnt(9)
	v_mov_b32_e32 v128, v214
	v_mov_b32_e32 v129, v215
	v_mov_b32_e32 v130, v216
	v_mov_b32_e32 v131, v217
	global_load_dwordx4 v[214:217], v[244:245], off offset:528
	global_store_dwordx4 v[150:151], v[160:163], off
	global_store_dwordx4 v[150:151], v[132:135], off offset:256
	s_waitcnt vmcnt(8)
	v_pk_fma_f32 v[116:117], v[116:117], v[76:77], v[120:121]
	v_pk_fma_f32 v[118:119], v[118:119], v[78:79], v[122:123]
	v_pk_fma_f32 v[112:113], v[112:113], v[64:65], v[128:129]
	v_cvt_pk_bf16_f32 v116, v116, v117
	v_cvt_pk_bf16_f32 v117, v118, v119
	v_cvt_pk_bf16_f32 v118, v112, v113
	v_add_co_u32_e32 v112, vcc, s0, v150
	v_pk_fma_f32 v[114:115], v[114:115], v[66:67], v[130:131]
	s_nop 0
	v_addc_co_u32_e32 v113, vcc, 0, v151, vcc
	v_cvt_pk_bf16_f32 v119, v114, v115
	s_mov_b32 s0, 0x20000
	global_store_dwordx4 v[112:113], v[124:127], off
	global_store_dwordx4 v[112:113], v[116:119], off offset:256
	v_lshl_add_u64 v[120:121], v[152:153], 0, s[20:21]
	v_add_co_u32_e32 v126, vcc, s0, v152
	s_mov_b64 s[20:21], 0x20200
	s_nop 0
	v_addc_co_u32_e32 v127, vcc, 0, v153, vcc
	s_waitcnt vmcnt(13)
	v_mov_b32_e32 v116, v172
	v_mov_b32_e32 v117, v173
	v_mov_b32_e32 v118, v174
	v_mov_b32_e32 v119, v175
	s_mov_b32 s98, 0x80000
	s_mov_b32 s99, 0
	v_lshl_add_u64 v[244:245], v[152:153], 0, s[98:99]
	global_load_dwordx4 v[172:175], v[244:245], off
	s_nop 0
	s_waitcnt vmcnt(13)
	v_mov_b32_e32 v120, v176
	v_mov_b32_e32 v121, v177
	v_mov_b32_e32 v122, v178
	v_mov_b32_e32 v123, v179
	global_load_dwordx4 v[176:179], v[244:245], off offset:16
	v_lshl_add_u64 v[124:125], v[152:153], 0, s[20:21]
	s_mov_b32 s0, 0x30000
	s_mov_b64 s[20:21], 0x30000
	v_lshl_add_u64 v[114:115], v[152:153], 0, s[20:21]
	s_mov_b64 s[20:21], 0x30200
	v_lshl_add_u64 v[112:113], v[152:153], 0, s[20:21]
	s_mov_b64 s[20:21], 0x80000
	s_waitcnt vmcnt(12)
	v_pk_fma_f32 v[108:109], v[108:109], v[72:73], v[116:117]
	v_pk_fma_f32 v[110:111], v[110:111], v[74:75], v[118:119]
	v_pk_fma_f32 v[104:105], v[104:105], v[68:69], v[120:121]
	v_cvt_pk_bf16_f32 v108, v108, v109
	v_cvt_pk_bf16_f32 v109, v110, v111
	v_cvt_pk_bf16_f32 v110, v104, v105
	v_pk_fma_f32 v[104:105], v[106:107], v[70:71], v[122:123]
	s_nop 0
	v_cvt_pk_bf16_f32 v111, v104, v105
	s_waitcnt vmcnt(11)
	v_mov_b32_e32 v104, v180
	v_mov_b32_e32 v105, v181
	v_mov_b32_e32 v106, v182
	v_mov_b32_e32 v107, v183
	global_load_dwordx4 v[180:183], v[244:245], off offset:512
	s_waitcnt vmcnt(11)
	v_mov_b32_e32 v116, v184
	v_mov_b32_e32 v117, v185
	v_mov_b32_e32 v118, v186
	v_mov_b32_e32 v119, v187
	global_load_dwordx4 v[184:187], v[244:245], off offset:528
	s_waitcnt vmcnt(14)
	v_pk_fma_f32 v[100:101], v[100:101], v[76:77], v[104:105]
	v_pk_fma_f32 v[102:103], v[102:103], v[78:79], v[106:107]
	v_pk_fma_f32 v[96:97], v[96:97], v[64:65], v[116:117]
	v_add_co_u32_e32 v116, vcc, s0, v152
	v_cvt_pk_bf16_f32 v100, v100, v101
	v_cvt_pk_bf16_f32 v101, v102, v103
	v_cvt_pk_bf16_f32 v102, v96, v97
	v_pk_fma_f32 v[96:97], v[98:99], v[66:67], v[118:119]
	v_addc_co_u32_e32 v117, vcc, 0, v153, vcc
	v_cvt_pk_bf16_f32 v103, v96, v97
	s_waitcnt vmcnt(11)
	v_mov_b32_e32 v96, v188
	v_mov_b32_e32 v97, v189
	v_mov_b32_e32 v98, v190
	v_mov_b32_e32 v99, v191
	s_mov_b32 s98, 0x90000
	s_mov_b32 s99, 0
	v_lshl_add_u64 v[244:245], v[152:153], 0, s[98:99]
	global_load_dwordx4 v[188:191], v[244:245], off
	s_waitcnt vmcnt(11)
	v_mov_b32_e32 v104, v206
	v_mov_b32_e32 v105, v207
	v_mov_b32_e32 v106, v208
	v_mov_b32_e32 v107, v209
	global_load_dwordx4 v[206:209], v[244:245], off offset:16
	s_mov_b32 s0, 0x18000
	s_waitcnt vmcnt(16)
	v_pk_fma_f32 v[92:93], v[92:93], v[72:73], v[96:97]
	v_pk_fma_f32 v[94:95], v[94:95], v[74:75], v[98:99]
	v_pk_fma_f32 v[88:89], v[88:89], v[68:69], v[104:105]
	v_cvt_pk_bf16_f32 v92, v92, v93
	v_cvt_pk_bf16_f32 v93, v94, v95
	v_cvt_pk_bf16_f32 v94, v88, v89
	v_pk_fma_f32 v[88:89], v[90:91], v[70:71], v[106:107]
	s_nop 0
	v_cvt_pk_bf16_f32 v95, v88, v89
	s_waitcnt vmcnt(11)
	v_mov_b32_e32 v88, v210
	v_mov_b32_e32 v89, v211
	v_mov_b32_e32 v90, v212
	v_mov_b32_e32 v91, v213
	global_load_dwordx4 v[210:213], v[244:245], off offset:512
	s_waitcnt vmcnt(11)
	v_mov_b32_e32 v96, v214
	v_mov_b32_e32 v97, v215
	v_mov_b32_e32 v98, v216
	v_mov_b32_e32 v99, v217
	global_load_dwordx4 v[214:217], v[244:245], off offset:528
	s_waitcnt vmcnt(18)
	v_pk_fma_f32 v[84:85], v[84:85], v[76:77], v[88:89]
	v_pk_fma_f32 v[86:87], v[86:87], v[78:79], v[90:91]
	v_pk_fma_f32 v[80:81], v[80:81], v[64:65], v[96:97]
	v_cvt_pk_bf16_f32 v84, v84, v85
	v_cvt_pk_bf16_f32 v85, v86, v87
	v_cvt_pk_bf16_f32 v86, v80, v81
	v_add_co_u32_e32 v80, vcc, s7, v150
	v_pk_fma_f32 v[82:83], v[82:83], v[66:67], v[98:99]
	s_nop 0
	v_addc_co_u32_e32 v81, vcc, 0, v151, vcc
	global_store_dwordx4 v[80:81], v[108:111], off
	global_store_dwordx4 v[80:81], v[100:103], off offset:256
	v_add_co_u32_e32 v80, vcc, s0, v150
	v_cvt_pk_bf16_f32 v87, v82, v83
	s_nop 0
	v_addc_co_u32_e32 v81, vcc, 0, v151, vcc
	s_mov_b32 s0, 0x80000
	global_store_dwordx4 v[80:81], v[92:95], off
	global_store_dwordx4 v[80:81], v[84:87], off offset:256
	v_add_co_u32_e32 v96, vcc, s0, v152
	v_lshl_add_u64 v[82:83], v[152:153], 0, s[20:21]
	s_nop 0
	v_addc_co_u32_e32 v97, vcc, 0, v153, vcc
	s_waitcnt vmcnt(11)
	v_mov_b32_e32 v86, v172
	v_mov_b32_e32 v87, v173
	v_mov_b32_e32 v88, v174
	v_mov_b32_e32 v89, v175
	s_mov_b32 s98, 0xa0000
	s_mov_b32 s99, 0
	v_lshl_add_u64 v[244:245], v[152:153], 0, s[98:99]
	global_load_dwordx4 v[172:175], v[244:245], off
	s_waitcnt vmcnt(11)
	v_mov_b32_e32 v90, v176
	v_mov_b32_e32 v91, v177
	v_mov_b32_e32 v92, v178
	v_mov_b32_e32 v93, v179
	global_load_dwordx4 v[176:179], v[244:245], off offset:16
	s_mov_b64 s[20:21], 0x80200
	v_lshl_add_u64 v[94:95], v[152:153], 0, s[20:21]
	s_mov_b32 s0, 0x90000
	v_add_co_u32_e32 v82, vcc, s0, v152
	s_mov_b64 s[20:21], 0x90000
	s_nop 0
	v_addc_co_u32_e32 v83, vcc, 0, v153, vcc
	v_lshl_add_u64 v[84:85], v[152:153], 0, s[20:21]
	s_mov_b64 s[20:21], 0x90200
	v_lshl_add_u64 v[80:81], v[152:153], 0, s[20:21]
	s_mov_b32 s0, 0x40000
	s_mov_b64 s[20:21], 0xa0000
	s_waitcnt vmcnt(24)
	v_pk_fma_f32 v[60:61], v[60:61], v[72:73], v[86:87]
	v_pk_fma_f32 v[62:63], v[62:63], v[74:75], v[88:89]
	v_pk_fma_f32 v[56:57], v[56:57], v[68:69], v[90:91]
	v_cvt_pk_bf16_f32 v60, v60, v61
	v_cvt_pk_bf16_f32 v61, v62, v63
	v_cvt_pk_bf16_f32 v62, v56, v57
	v_pk_fma_f32 v[56:57], v[58:59], v[70:71], v[92:93]
	s_nop 0
	v_cvt_pk_bf16_f32 v63, v56, v57
	s_waitcnt vmcnt(11)
	v_mov_b32_e32 v56, v180
	v_mov_b32_e32 v57, v181
	v_mov_b32_e32 v58, v182
	v_mov_b32_e32 v59, v183
	global_load_dwordx4 v[180:183], v[244:245], off offset:512
	s_waitcnt vmcnt(11)
	v_mov_b32_e32 v86, v184
	v_mov_b32_e32 v87, v185
	v_mov_b32_e32 v88, v186
	v_mov_b32_e32 v89, v187
	global_load_dwordx4 v[184:187], v[244:245], off offset:528
	s_waitcnt vmcnt(26)
	v_pk_fma_f32 v[52:53], v[52:53], v[76:77], v[56:57]
	v_pk_fma_f32 v[54:55], v[54:55], v[78:79], v[58:59]
	v_pk_fma_f32 v[48:49], v[48:49], v[64:65], v[86:87]
	v_cvt_pk_bf16_f32 v52, v52, v53
	v_cvt_pk_bf16_f32 v53, v54, v55
	v_cvt_pk_bf16_f32 v54, v48, v49
	v_pk_fma_f32 v[48:49], v[50:51], v[66:67], v[88:89]
	s_nop 0
	v_cvt_pk_bf16_f32 v55, v48, v49
	s_waitcnt vmcnt(11)
	v_mov_b32_e32 v48, v188
	v_mov_b32_e32 v49, v189
	v_mov_b32_e32 v50, v190
	v_mov_b32_e32 v51, v191
	s_mov_b32 s98, 0xb0000
	s_mov_b32 s99, 0
	v_lshl_add_u64 v[244:245], v[152:153], 0, s[98:99]
	global_load_dwordx4 v[188:191], v[244:245], off
	s_waitcnt vmcnt(11)
	v_mov_b32_e32 v56, v206
	v_mov_b32_e32 v57, v207
	v_mov_b32_e32 v58, v208
	v_mov_b32_e32 v59, v209
	global_load_dwordx4 v[206:209], v[244:245], off offset:16
	s_waitcnt vmcnt(28)
	v_pk_fma_f32 v[44:45], v[44:45], v[72:73], v[48:49]
	v_pk_fma_f32 v[46:47], v[46:47], v[74:75], v[50:51]
	v_pk_fma_f32 v[40:41], v[40:41], v[68:69], v[56:57]
	v_cvt_pk_bf16_f32 v44, v44, v45
	v_cvt_pk_bf16_f32 v45, v46, v47
	v_cvt_pk_bf16_f32 v46, v40, v41
	v_pk_fma_f32 v[40:41], v[42:43], v[70:71], v[58:59]
	s_nop 0
	v_cvt_pk_bf16_f32 v47, v40, v41
	s_waitcnt vmcnt(11)
	v_mov_b32_e32 v40, v210
	v_mov_b32_e32 v41, v211
	v_mov_b32_e32 v42, v212
	v_mov_b32_e32 v43, v213
	global_load_dwordx4 v[210:213], v[244:245], off offset:512
	s_waitcnt vmcnt(11)
	v_mov_b32_e32 v48, v214
	v_mov_b32_e32 v49, v215
	v_mov_b32_e32 v50, v216
	v_mov_b32_e32 v51, v217
	global_load_dwordx4 v[214:217], v[244:245], off offset:528
	s_waitcnt vmcnt(30)
	v_pk_fma_f32 v[36:37], v[36:37], v[76:77], v[40:41]
	v_pk_fma_f32 v[38:39], v[38:39], v[78:79], v[42:43]
	v_pk_fma_f32 v[32:33], v[32:33], v[64:65], v[48:49]
	v_cvt_pk_bf16_f32 v36, v36, v37
	v_cvt_pk_bf16_f32 v37, v38, v39
	v_cvt_pk_bf16_f32 v38, v32, v33
	v_add_co_u32_e32 v32, vcc, s0, v150
	s_mov_b32 s0, 0x48000
	s_nop 0
	v_addc_co_u32_e32 v33, vcc, 0, v151, vcc
	global_store_dwordx4 v[32:33], v[60:63], off
	global_store_dwordx4 v[32:33], v[52:55], off offset:256
	v_add_co_u32_e32 v32, vcc, s0, v150
	v_pk_fma_f32 v[34:35], v[34:35], v[66:67], v[50:51]
	s_nop 0
	v_addc_co_u32_e32 v33, vcc, 0, v151, vcc
	v_cvt_pk_bf16_f32 v39, v34, v35
	s_mov_b32 s0, 0xa0000
	global_store_dwordx4 v[32:33], v[44:47], off
	global_store_dwordx4 v[32:33], v[36:39], off offset:256
	v_lshl_add_u64 v[40:41], v[152:153], 0, s[20:21]
	v_add_co_u32_e32 v46, vcc, s0, v152
	s_mov_b64 s[20:21], 0xa0200
	s_nop 0
	v_addc_co_u32_e32 v47, vcc, 0, v153, vcc
	s_waitcnt vmcnt(11)
	v_mov_b32_e32 v36, v172
	v_mov_b32_e32 v37, v173
	v_mov_b32_e32 v38, v174
	v_mov_b32_e32 v39, v175
	s_nop 0
	s_waitcnt vmcnt(10)
	v_mov_b32_e32 v40, v176
	v_mov_b32_e32 v41, v177
	v_mov_b32_e32 v42, v178
	v_mov_b32_e32 v43, v179
	v_lshl_add_u64 v[44:45], v[152:153], 0, s[20:21]
	s_mov_b32 s0, 0xb0000
	s_mov_b64 s[20:21], 0xb0000
	v_lshl_add_u64 v[34:35], v[152:153], 0, s[20:21]
	s_mov_b64 s[20:21], 0xb0200
	v_lshl_add_u64 v[32:33], v[152:153], 0, s[20:21]
	s_mov_b64 s[20:21], s[14:15]
	s_waitcnt vmcnt(34)
	v_pk_fma_f32 v[28:29], v[28:29], v[72:73], v[36:37]
	v_pk_fma_f32 v[30:31], v[30:31], v[74:75], v[38:39]
	v_pk_fma_f32 v[24:25], v[24:25], v[68:69], v[40:41]
	v_cvt_pk_bf16_f32 v28, v28, v29
	v_cvt_pk_bf16_f32 v29, v30, v31
	v_cvt_pk_bf16_f32 v30, v24, v25
	v_pk_fma_f32 v[24:25], v[26:27], v[70:71], v[42:43]
	s_nop 0
	v_cvt_pk_bf16_f32 v31, v24, v25
	s_waitcnt vmcnt(9)
	v_mov_b32_e32 v24, v180
	v_mov_b32_e32 v25, v181
	v_mov_b32_e32 v26, v182
	v_mov_b32_e32 v27, v183
	s_waitcnt vmcnt(8)
	v_mov_b32_e32 v36, v184
	v_mov_b32_e32 v37, v185
	v_mov_b32_e32 v38, v186
	v_mov_b32_e32 v39, v187
	s_waitcnt vmcnt(34)
	v_pk_fma_f32 v[20:21], v[20:21], v[76:77], v[24:25]
	v_pk_fma_f32 v[22:23], v[22:23], v[78:79], v[26:27]
	v_pk_fma_f32 v[16:17], v[16:17], v[64:65], v[36:37]
	v_add_co_u32_e32 v36, vcc, s0, v152
	v_cvt_pk_bf16_f32 v20, v20, v21
	v_cvt_pk_bf16_f32 v21, v22, v23
	v_cvt_pk_bf16_f32 v22, v16, v17
	v_pk_fma_f32 v[16:17], v[18:19], v[66:67], v[38:39]
	v_addc_co_u32_e32 v37, vcc, 0, v153, vcc
	v_cvt_pk_bf16_f32 v23, v16, v17
	s_waitcnt vmcnt(7)
	v_mov_b32_e32 v16, v188
	v_mov_b32_e32 v17, v189
	v_mov_b32_e32 v18, v190
	v_mov_b32_e32 v19, v191
	s_waitcnt vmcnt(6)
	v_mov_b32_e32 v24, v206
	v_mov_b32_e32 v25, v207
	v_mov_b32_e32 v26, v208
	v_mov_b32_e32 v27, v209
	s_mov_b32 s0, 0x50000
	s_waitcnt vmcnt(34)
	v_pk_fma_f32 v[12:13], v[12:13], v[72:73], v[16:17]
	v_pk_fma_f32 v[14:15], v[14:15], v[74:75], v[18:19]
	v_pk_fma_f32 v[8:9], v[8:9], v[68:69], v[24:25]
	v_cvt_pk_bf16_f32 v12, v12, v13
	v_cvt_pk_bf16_f32 v13, v14, v15
	v_cvt_pk_bf16_f32 v14, v8, v9
	v_pk_fma_f32 v[8:9], v[10:11], v[70:71], v[26:27]
	s_nop 0
	v_cvt_pk_bf16_f32 v15, v8, v9
	s_waitcnt vmcnt(5)
	v_mov_b32_e32 v8, v210
	v_mov_b32_e32 v9, v211
	v_mov_b32_e32 v10, v212
	v_mov_b32_e32 v11, v213
	s_waitcnt vmcnt(4)
	v_mov_b32_e32 v16, v214
	v_mov_b32_e32 v17, v215
	v_mov_b32_e32 v18, v216
	v_mov_b32_e32 v19, v217
	s_waitcnt vmcnt(34)
	v_pk_fma_f32 v[4:5], v[4:5], v[76:77], v[8:9]
	v_pk_fma_f32 v[6:7], v[6:7], v[78:79], v[10:11]
	v_pk_fma_f32 v[0:1], v[0:1], v[64:65], v[16:17]
	v_cvt_pk_bf16_f32 v4, v4, v5
	v_cvt_pk_bf16_f32 v5, v6, v7
	v_cvt_pk_bf16_f32 v6, v0, v1
	v_add_co_u32_e32 v0, vcc, s0, v150
	v_pk_fma_f32 v[2:3], v[2:3], v[66:67], v[18:19]
	s_nop 0
	v_addc_co_u32_e32 v1, vcc, 0, v151, vcc
	global_store_dwordx4 v[0:1], v[28:31], off
	global_store_dwordx4 v[0:1], v[20:23], off offset:256
	v_add_co_u32_e32 v0, vcc, 0x58000, v150
	v_cvt_pk_bf16_f32 v7, v2, v3
	s_nop 0
	v_addc_co_u32_e32 v1, vcc, 0, v151, vcc
	global_store_dwordx4 v[0:1], v[12:15], off
	global_store_dwordx4 v[0:1], v[4:7], off offset:256
	s_and_b64 vcc, exec, s[2:3]
	s_cbranch_vccz .LBB0_988
	s_waitcnt vmcnt(0)
	s_cmpk_gt_u32 s4, 0xff
	s_cbranch_scc1 .LBB0_995
	s_barrier
